# one static s_setprio 1 for waves 4-7 at the phase-loop head; the 96 per-MMA-group s_setprio flips in the 6 K-loops deleted
# speedup vs baseline: 1.0162x; 1.0059x over previous
.LBB0_24:
	v_readlane_b32 s48, v253, 16
	s_mov_b64 s[82:83], 0x60000
	s_movk_i32 s90, 0x104
	v_readfirstlane_b32 s2, v193
	s_nop 1
	s_cmpk_gt_u32 s2, 0xff
	s_cbranch_scc0 .Lprio_skip
	s_setprio 1
.Lprio_skip:
	s_mov_b64 s[28:29], -1
	s_mov_b64 s[0:1], 0
	s_cmp_lt_i32 s84, 1
	s_mov_b64 s[22:23], 0
	v_readlane_b32 s49, v253, 17
	v_readlane_b32 s50, v253, 18
	v_readlane_b32 s51, v253, 19
	v_readlane_b32 s52, v253, 20
	v_readlane_b32 s53, v253, 21
	v_readlane_b32 s54, v253, 22
	v_readlane_b32 s55, v253, 23
	v_readlane_b32 s56, v253, 24
	v_readlane_b32 s57, v253, 25
	v_readlane_b32 s58, v253, 26
	v_readlane_b32 s59, v253, 27
	v_readlane_b32 s60, v253, 28
	v_readlane_b32 s61, v253, 29
	v_readlane_b32 s62, v253, 30
	v_readlane_b32 s63, v253, 31
	s_cbranch_scc0 .LBB0_27
	s_and_b64 vcc, exec, s[28:29]
	s_cbranch_vccnz .LBB0_37

.LBB0_66:
	v_or_b32_e32 v142, 0x10000, v140
	v_add_u32_e32 v146, 0x10400, v140
	v_add_u32_e32 v150, 0x10800, v140
	v_add_u32_e32 v154, 0x10c00, v140
	ds_read_b128 v[142:145], v142
	ds_read_b128 v[146:149], v146
	ds_read_b128 v[150:153], v150
	ds_read_b128 v[154:157], v154
	s_add_u32 s42, s40, 0xfffc0080
	s_addc_u32 s43, s41, -1
	s_cmp_eq_u32 s96, 12
	s_cselect_b32 s45, s31, s43
	s_cselect_b32 s44, s80, s42
	s_cselect_b32 s43, s29, s27
	s_cselect_b32 s42, vcc_lo, s26
	s_mov_b32 m0, s69
	v_lshl_add_u64 v[182:183], s[40:41], 0, v[134:135]
	ds_read_b128 v[158:161], v139
	ds_read_b128 v[162:165], v139 offset:1024
	ds_read_b128 v[166:169], v139 offset:2048
	ds_read_b128 v[170:173], v139 offset:3072
	ds_read_b128 v[174:177], v139 offset:4096
	ds_read_b128 v[178:181], v139 offset:5120
	ds_read_b128 v[186:189], v139 offset:6144
	ds_read_b128 v[194:197], v139 offset:7168
	global_load_lds_dwordx4 v[182:183], off
	v_lshl_add_u64 v[182:183], s[40:41], 0, v[136:137]
	s_mov_b32 m0, s70
	s_nop 0
	global_load_lds_dwordx4 v[182:183], off
	s_waitcnt lgkmcnt(8)
	s_barrier
	s_waitcnt lgkmcnt(0)
	s_waitcnt lgkmcnt(0)
	v_mfma_f32_16x16x32_bf16 v[124:127], v[142:145], v[158:161], v[124:127]
	v_mfma_f32_16x16x32_bf16 v[116:119], v[150:153], v[158:161], v[116:119]
	v_mfma_f32_16x16x32_bf16 v[108:111], v[142:145], v[166:169], v[108:111]
	v_mfma_f32_16x16x32_bf16 v[100:103], v[150:153], v[166:169], v[100:103]
	v_mfma_f32_16x16x32_bf16 v[92:95], v[142:145], v[174:177], v[92:95]
	v_mfma_f32_16x16x32_bf16 v[84:87], v[150:153], v[174:177], v[84:87]
	v_mfma_f32_16x16x32_bf16 v[76:79], v[142:145], v[186:189], v[76:79]
	v_mfma_f32_16x16x32_bf16 v[68:71], v[150:153], v[186:189], v[68:71]
	v_mfma_f32_16x16x32_bf16 v[124:127], v[146:149], v[162:165], v[124:127]
	v_mfma_f32_16x16x32_bf16 v[116:119], v[154:157], v[162:165], v[116:119]
	v_mfma_f32_16x16x32_bf16 v[108:111], v[146:149], v[170:173], v[108:111]
	v_mfma_f32_16x16x32_bf16 v[100:103], v[154:157], v[170:173], v[100:103]
	v_mfma_f32_16x16x32_bf16 v[92:95], v[146:149], v[178:181], v[92:95]
	v_mfma_f32_16x16x32_bf16 v[84:87], v[154:157], v[178:181], v[84:87]
	v_mfma_f32_16x16x32_bf16 v[76:79], v[146:149], v[194:197], v[76:79]
	v_mfma_f32_16x16x32_bf16 v[68:71], v[154:157], v[194:197], v[68:71]
	s_barrier
	v_or_b32_e32 v182, 0x14000, v140
	v_add_u32_e32 v183, 0x14400, v140
	ds_read_b128 v[198:201], v182
	ds_read_b128 v[202:205], v183
	v_add_u32_e32 v182, 0x14800, v140
	v_add_u32_e32 v183, 0x14c00, v140
	s_mov_b32 m0, s39
	ds_read_b128 v[206:209], v182
	ds_read_b128 v[210:213], v183
	v_lshl_add_u64 v[182:183], s[42:43], 0, v[184:185]
	global_load_lds_dwordx4 v[182:183], off
	v_lshl_add_u64 v[190:191], s[42:43], 0, v[128:129]
	s_mov_b32 m0, s53
	s_nop 0
	global_load_lds_dwordx4 v[190:191], off
	s_barrier
	s_waitcnt lgkmcnt(0)
	s_waitcnt lgkmcnt(0)
	v_mfma_f32_16x16x32_bf16 v[120:123], v[198:201], v[158:161], v[120:123]
	v_mfma_f32_16x16x32_bf16 v[112:115], v[206:209], v[158:161], v[112:115]
	v_mfma_f32_16x16x32_bf16 v[104:107], v[198:201], v[166:169], v[104:107]
	v_mfma_f32_16x16x32_bf16 v[96:99], v[206:209], v[166:169], v[96:99]
	v_mfma_f32_16x16x32_bf16 v[88:91], v[198:201], v[174:177], v[88:91]
	v_mfma_f32_16x16x32_bf16 v[80:83], v[206:209], v[174:177], v[80:83]
	v_mfma_f32_16x16x32_bf16 v[72:75], v[198:201], v[186:189], v[72:75]
	v_mfma_f32_16x16x32_bf16 v[64:67], v[206:209], v[186:189], v[64:67]
	v_mfma_f32_16x16x32_bf16 v[120:123], v[202:205], v[162:165], v[120:123]
	v_mfma_f32_16x16x32_bf16 v[112:115], v[210:213], v[162:165], v[112:115]
	v_mfma_f32_16x16x32_bf16 v[104:107], v[202:205], v[170:173], v[104:107]
	v_mfma_f32_16x16x32_bf16 v[96:99], v[210:213], v[170:173], v[96:99]
	v_mfma_f32_16x16x32_bf16 v[88:91], v[202:205], v[178:181], v[88:91]
	v_mfma_f32_16x16x32_bf16 v[80:83], v[210:213], v[178:181], v[80:83]
	v_mfma_f32_16x16x32_bf16 v[72:75], v[202:205], v[194:197], v[72:75]
	v_mfma_f32_16x16x32_bf16 v[64:67], v[210:213], v[194:197], v[64:67]
	s_mov_b32 m0, s50
	v_lshl_add_u64 v[214:215], s[44:45], 0, v[132:133]
	s_barrier
	ds_read_b128 v[158:161], v139 offset:16384
	ds_read_b128 v[162:165], v139 offset:17408
	ds_read_b128 v[166:169], v139 offset:18432
	ds_read_b128 v[170:173], v139 offset:19456
	ds_read_b128 v[174:177], v139 offset:20480
	ds_read_b128 v[178:181], v139 offset:21504
	ds_read_b128 v[186:189], v139 offset:22528
	ds_read_b128 v[194:197], v139 offset:23552
	global_load_lds_dwordx4 v[214:215], off
	v_lshl_add_u64 v[216:217], s[44:45], 0, v[130:131]
	s_mov_b32 m0, s54
	s_nop 0
	global_load_lds_dwordx4 v[216:217], off
	s_barrier
	s_waitcnt lgkmcnt(0)
	s_waitcnt lgkmcnt(0)
	s_cmp_lg_u32 s100, 0
	s_cbranch_scc1 .Luph_s2
	v_mfma_f32_16x16x32_bf16 v[60:63], v[142:145], v[158:161], v[60:63]
	v_mfma_f32_16x16x32_bf16 v[52:55], v[150:153], v[158:161], v[52:55]
	v_mfma_f32_16x16x32_bf16 v[44:47], v[142:145], v[166:169], v[44:47]
	v_mfma_f32_16x16x32_bf16 v[36:39], v[150:153], v[166:169], v[36:39]
	v_mfma_f32_16x16x32_bf16 v[28:31], v[142:145], v[174:177], v[28:31]
	v_mfma_f32_16x16x32_bf16 v[20:23], v[150:153], v[174:177], v[20:23]
	v_mfma_f32_16x16x32_bf16 v[12:15], v[142:145], v[186:189], v[12:15]
	v_mfma_f32_16x16x32_bf16 v[4:7], v[150:153], v[186:189], v[4:7]
	v_mfma_f32_16x16x32_bf16 v[60:63], v[146:149], v[162:165], v[60:63]
	v_mfma_f32_16x16x32_bf16 v[52:55], v[154:157], v[162:165], v[52:55]
	v_mfma_f32_16x16x32_bf16 v[44:47], v[146:149], v[170:173], v[44:47]
	v_mfma_f32_16x16x32_bf16 v[36:39], v[154:157], v[170:173], v[36:39]
	v_mfma_f32_16x16x32_bf16 v[28:31], v[146:149], v[178:181], v[28:31]
	v_mfma_f32_16x16x32_bf16 v[20:23], v[154:157], v[178:181], v[20:23]
	v_mfma_f32_16x16x32_bf16 v[12:15], v[146:149], v[194:197], v[12:15]
	v_mfma_f32_16x16x32_bf16 v[4:7], v[154:157], v[194:197], v[4:7]
.Luph_s2:
	s_barrier
	s_add_u32 s66, s42, 0x40000
	s_addc_u32 s67, s43, 0
	s_mov_b32 m0, s55
	v_lshl_add_u64 v[142:143], s[66:67], 0, v[184:185]
	global_load_lds_dwordx4 v[142:143], off
	v_lshl_add_u64 v[142:143], s[66:67], 0, v[128:129]
	s_mov_b32 m0, s58
	s_nop 0
	global_load_lds_dwordx4 v[142:143], off
	s_waitcnt vmcnt(6)
	s_barrier
	s_cmp_lg_u32 s100, 0
	s_cbranch_scc1 .Luph_s3
	v_mfma_f32_16x16x32_bf16 v[56:59], v[198:201], v[158:161], v[56:59]
	v_mfma_f32_16x16x32_bf16 v[48:51], v[206:209], v[158:161], v[48:51]
	v_mfma_f32_16x16x32_bf16 v[40:43], v[198:201], v[166:169], v[40:43]
	v_mfma_f32_16x16x32_bf16 v[32:35], v[206:209], v[166:169], v[32:35]
	v_mfma_f32_16x16x32_bf16 v[24:27], v[198:201], v[174:177], v[24:27]
	v_mfma_f32_16x16x32_bf16 v[16:19], v[206:209], v[174:177], v[16:19]
	v_mfma_f32_16x16x32_bf16 v[8:11], v[198:201], v[186:189], v[8:11]
	v_mfma_f32_16x16x32_bf16 v[0:3], v[206:209], v[186:189], v[0:3]
	v_mfma_f32_16x16x32_bf16 v[56:59], v[202:205], v[162:165], v[56:59]
	v_mfma_f32_16x16x32_bf16 v[48:51], v[210:213], v[162:165], v[48:51]
	v_mfma_f32_16x16x32_bf16 v[40:43], v[202:205], v[170:173], v[40:43]
	v_mfma_f32_16x16x32_bf16 v[32:35], v[210:213], v[170:173], v[32:35]
	v_mfma_f32_16x16x32_bf16 v[24:27], v[202:205], v[178:181], v[24:27]
	v_mfma_f32_16x16x32_bf16 v[16:19], v[210:213], v[178:181], v[16:19]
	v_mfma_f32_16x16x32_bf16 v[8:11], v[202:205], v[194:197], v[8:11]
	v_mfma_f32_16x16x32_bf16 v[0:3], v[210:213], v[194:197], v[0:3]
.Luph_s3:
	v_or_b32_e32 v142, 0x18000, v140
	v_add_u32_e32 v146, 0x18400, v140
	v_add_u32_e32 v150, 0x18800, v140
	v_add_u32_e32 v154, 0x18c00, v140
	s_barrier
	ds_read_b128 v[142:145], v142
	ds_read_b128 v[146:149], v146
	ds_read_b128 v[150:153], v150
	ds_read_b128 v[154:157], v154
	s_add_u32 s44, s44, 0x40000
	s_addc_u32 s45, s45, 0
	s_mov_b32 m0, s59
	v_lshl_add_u64 v[198:199], s[44:45], 0, v[132:133]
	ds_read_b128 v[158:161], v139 offset:32768
	ds_read_b128 v[162:165], v139 offset:33792
	ds_read_b128 v[166:169], v139 offset:34816
	ds_read_b128 v[170:173], v139 offset:35840
	ds_read_b128 v[174:177], v139 offset:36864
	ds_read_b128 v[178:181], v139 offset:37888
	ds_read_b128 v[186:189], v139 offset:38912
	ds_read_b128 v[194:197], v139 offset:39936
	global_load_lds_dwordx4 v[198:199], off
	v_lshl_add_u64 v[198:199], s[44:45], 0, v[130:131]
	s_mov_b32 m0, s60
	s_nop 0
	global_load_lds_dwordx4 v[198:199], off
	s_waitcnt lgkmcnt(8)
	s_barrier
	s_waitcnt lgkmcnt(0)
	s_waitcnt lgkmcnt(0)
	v_mfma_f32_16x16x32_bf16 v[124:127], v[142:145], v[158:161], v[124:127]
	v_mfma_f32_16x16x32_bf16 v[116:119], v[150:153], v[158:161], v[116:119]
	v_mfma_f32_16x16x32_bf16 v[108:111], v[142:145], v[166:169], v[108:111]
	v_mfma_f32_16x16x32_bf16 v[100:103], v[150:153], v[166:169], v[100:103]
	v_mfma_f32_16x16x32_bf16 v[92:95], v[142:145], v[174:177], v[92:95]
	v_mfma_f32_16x16x32_bf16 v[84:87], v[150:153], v[174:177], v[84:87]
	v_mfma_f32_16x16x32_bf16 v[76:79], v[142:145], v[186:189], v[76:79]
	v_mfma_f32_16x16x32_bf16 v[68:71], v[150:153], v[186:189], v[68:71]
	v_mfma_f32_16x16x32_bf16 v[124:127], v[146:149], v[162:165], v[124:127]
	v_mfma_f32_16x16x32_bf16 v[116:119], v[154:157], v[162:165], v[116:119]
	v_mfma_f32_16x16x32_bf16 v[108:111], v[146:149], v[170:173], v[108:111]
	v_mfma_f32_16x16x32_bf16 v[100:103], v[154:157], v[170:173], v[100:103]
	v_mfma_f32_16x16x32_bf16 v[92:95], v[146:149], v[178:181], v[92:95]
	v_mfma_f32_16x16x32_bf16 v[84:87], v[154:157], v[178:181], v[84:87]
	v_mfma_f32_16x16x32_bf16 v[76:79], v[146:149], v[194:197], v[76:79]
	v_mfma_f32_16x16x32_bf16 v[68:71], v[154:157], v[194:197], v[68:71]
	s_barrier
	v_or_b32_e32 v192, 0x1c000, v140
	v_add_u32_e32 v202, 0x1c400, v140
	s_mov_b32 m0, s33
	ds_read_b128 v[198:201], v192
	ds_read_b128 v[202:205], v202
	v_add_u32_e32 v192, 0x1c800, v140
	v_add_u32_e32 v210, 0x1cc00, v140
	v_lshl_add_u64 v[182:183], v[182:183], 0, s[24:25]
	ds_read_b128 v[206:209], v192
	ds_read_b128 v[210:213], v210
	global_load_lds_dwordx4 v[182:183], off
	v_lshl_add_u64 v[182:183], v[190:191], 0, s[24:25]
	s_mov_b32 m0, s61
	s_nop 0
	global_load_lds_dwordx4 v[182:183], off
	s_barrier
	s_waitcnt lgkmcnt(0)
	s_waitcnt lgkmcnt(0)
	v_mfma_f32_16x16x32_bf16 v[120:123], v[198:201], v[158:161], v[120:123]
	v_mfma_f32_16x16x32_bf16 v[112:115], v[206:209], v[158:161], v[112:115]
	v_mfma_f32_16x16x32_bf16 v[104:107], v[198:201], v[166:169], v[104:107]
	v_mfma_f32_16x16x32_bf16 v[96:99], v[206:209], v[166:169], v[96:99]
	v_mfma_f32_16x16x32_bf16 v[88:91], v[198:201], v[174:177], v[88:91]
	v_mfma_f32_16x16x32_bf16 v[80:83], v[206:209], v[174:177], v[80:83]
	v_mfma_f32_16x16x32_bf16 v[72:75], v[198:201], v[186:189], v[72:75]
	v_mfma_f32_16x16x32_bf16 v[64:67], v[206:209], v[186:189], v[64:67]
	v_mfma_f32_16x16x32_bf16 v[120:123], v[202:205], v[162:165], v[120:123]
	v_mfma_f32_16x16x32_bf16 v[112:115], v[210:213], v[162:165], v[112:115]
	v_mfma_f32_16x16x32_bf16 v[104:107], v[202:205], v[170:173], v[104:107]
	v_mfma_f32_16x16x32_bf16 v[96:99], v[210:213], v[170:173], v[96:99]
	v_mfma_f32_16x16x32_bf16 v[88:91], v[202:205], v[178:181], v[88:91]
	v_mfma_f32_16x16x32_bf16 v[80:83], v[210:213], v[178:181], v[80:83]
	v_mfma_f32_16x16x32_bf16 v[72:75], v[202:205], v[194:197], v[72:75]
	v_mfma_f32_16x16x32_bf16 v[64:67], v[210:213], v[194:197], v[64:67]
	s_mov_b32 m0, s62
	v_lshl_add_u64 v[182:183], v[214:215], 0, s[24:25]
	s_barrier
	ds_read_b128 v[158:161], v139 offset:49152
	ds_read_b128 v[162:165], v139 offset:50176
	ds_read_b128 v[166:169], v139 offset:51200
	ds_read_b128 v[170:173], v139 offset:52224
	ds_read_b128 v[174:177], v139 offset:53248
	ds_read_b128 v[178:181], v139 offset:54272
	ds_read_b128 v[186:189], v139 offset:55296
	ds_read_b128 v[194:197], v139 offset:56320
	global_load_lds_dwordx4 v[182:183], off
	v_lshl_add_u64 v[182:183], v[216:217], 0, s[24:25]
	s_mov_b32 m0, s63
	s_nop 0
	global_load_lds_dwordx4 v[182:183], off
	s_barrier
	s_waitcnt lgkmcnt(0)
	s_waitcnt lgkmcnt(0)
	s_cmp_lg_u32 s100, 0
	s_cbranch_scc1 .Luph_s6
	v_mfma_f32_16x16x32_bf16 v[60:63], v[142:145], v[158:161], v[60:63]
	v_mfma_f32_16x16x32_bf16 v[52:55], v[150:153], v[158:161], v[52:55]
	v_mfma_f32_16x16x32_bf16 v[44:47], v[142:145], v[166:169], v[44:47]
	v_mfma_f32_16x16x32_bf16 v[36:39], v[150:153], v[166:169], v[36:39]
	v_mfma_f32_16x16x32_bf16 v[28:31], v[142:145], v[174:177], v[28:31]
	v_mfma_f32_16x16x32_bf16 v[20:23], v[150:153], v[174:177], v[20:23]
	v_mfma_f32_16x16x32_bf16 v[12:15], v[142:145], v[186:189], v[12:15]
	v_mfma_f32_16x16x32_bf16 v[4:7], v[150:153], v[186:189], v[4:7]
	v_mfma_f32_16x16x32_bf16 v[60:63], v[146:149], v[162:165], v[60:63]
	v_mfma_f32_16x16x32_bf16 v[52:55], v[154:157], v[162:165], v[52:55]
	v_mfma_f32_16x16x32_bf16 v[44:47], v[146:149], v[170:173], v[44:47]
	v_mfma_f32_16x16x32_bf16 v[36:39], v[154:157], v[170:173], v[36:39]
	v_mfma_f32_16x16x32_bf16 v[28:31], v[146:149], v[178:181], v[28:31]
	v_mfma_f32_16x16x32_bf16 v[20:23], v[154:157], v[178:181], v[20:23]
	v_mfma_f32_16x16x32_bf16 v[12:15], v[146:149], v[194:197], v[12:15]
	v_mfma_f32_16x16x32_bf16 v[4:7], v[154:157], v[194:197], v[4:7]
.Luph_s6:
	s_barrier
	s_add_u32 s42, s42, 0x40080
	s_addc_u32 s43, s43, 0
	s_mov_b32 m0, s64
	v_lshl_add_u64 v[142:143], s[42:43], 0, v[184:185]
	global_load_lds_dwordx4 v[142:143], off
	v_lshl_add_u64 v[142:143], s[42:43], 0, v[128:129]
	s_mov_b32 m0, s65
	s_nop 0
	global_load_lds_dwordx4 v[142:143], off
	s_waitcnt vmcnt(6)
	s_barrier
	s_cmp_lg_u32 s100, 0
	s_cbranch_scc1 .Luph_s7
	v_mfma_f32_16x16x32_bf16 v[56:59], v[198:201], v[158:161], v[56:59]
	v_mfma_f32_16x16x32_bf16 v[48:51], v[206:209], v[158:161], v[48:51]
	v_mfma_f32_16x16x32_bf16 v[40:43], v[198:201], v[166:169], v[40:43]
	v_mfma_f32_16x16x32_bf16 v[32:35], v[206:209], v[166:169], v[32:35]
	v_mfma_f32_16x16x32_bf16 v[24:27], v[198:201], v[174:177], v[24:27]
	v_mfma_f32_16x16x32_bf16 v[16:19], v[206:209], v[174:177], v[16:19]
	v_mfma_f32_16x16x32_bf16 v[8:11], v[198:201], v[186:189], v[8:11]
	v_mfma_f32_16x16x32_bf16 v[0:3], v[206:209], v[186:189], v[0:3]
	v_mfma_f32_16x16x32_bf16 v[56:59], v[202:205], v[162:165], v[56:59]
	v_mfma_f32_16x16x32_bf16 v[48:51], v[210:213], v[162:165], v[48:51]
	v_mfma_f32_16x16x32_bf16 v[40:43], v[202:205], v[170:173], v[40:43]
	v_mfma_f32_16x16x32_bf16 v[32:35], v[210:213], v[170:173], v[32:35]
	v_mfma_f32_16x16x32_bf16 v[24:27], v[202:205], v[178:181], v[24:27]
	v_mfma_f32_16x16x32_bf16 v[16:19], v[210:213], v[178:181], v[16:19]
	v_mfma_f32_16x16x32_bf16 v[8:11], v[202:205], v[194:197], v[8:11]
	v_mfma_f32_16x16x32_bf16 v[0:3], v[210:213], v[194:197], v[0:3]
.Luph_s7:
	s_add_i32 s96, s96, 2
	s_add_u32 s40, s40, 0x100
	s_addc_u32 s41, s41, 0
	s_add_u32 s26, s26, 0x100
	s_addc_u32 s27, s27, 0
	s_cmp_gt_u32 s96, 13
	s_barrier
	s_cbranch_scc0 .LBB0_66
	v_mul_f32_e32 v143, 0xbfb8aa3b, v124
	v_exp_f32_e32 v143, v143
	v_readlane_b32 s4, v254, 2
	v_lshl_or_b32 v144, s71, 7, v141
	v_readlane_b32 s5, v254, 3
	v_add_f32_e32 v143, 1.0, v143
	v_rcp_f32_e32 v143, v143
	v_lshl_add_u32 v142, s38, 8, v138
	s_cmp_eq_u32 s100, 2
	s_cbranch_scc0 .Luph_noshift
	v_add_u32_e32 v142, 0x80, v142

.LBB0_94:
	v_or_b32_e32 v138, 0x10000, v142
	v_add_u32_e32 v139, 0x10400, v142
	ds_read_b128 v[144:147], v138
	ds_read_b128 v[148:151], v139
	v_add_u32_e32 v138, 0x10800, v142
	s_add_i32 s71, s34, 2
	v_add_u32_e32 v139, 0x10c00, v142
	ds_read_b128 v[152:155], v138
	ds_read_b128 v[156:159], v139
	s_add_u32 s36, s30, 0x80
	s_addc_u32 s35, s31, 0
	s_cmp_eq_u32 s63, s34
	s_cselect_b32 s34, s28, s36
	s_cselect_b32 s35, s29, s35
	s_cselect_b32 s37, s1, s27
	s_cselect_b32 s36, s0, s26
	v_lshl_add_u64 v[138:139], s[30:31], 0, v[134:135]
	s_add_i32 m0, s44, 0xc000
	ds_read_b128 v[160:163], v141
	ds_read_b128 v[164:167], v141 offset:1024
	ds_read_b128 v[168:171], v141 offset:2048
	ds_read_b128 v[172:175], v141 offset:3072
	ds_read_b128 v[176:179], v141 offset:4096
	ds_read_b128 v[180:183], v141 offset:5120
	ds_read_b128 v[186:189], v141 offset:6144
	ds_read_b128 v[194:197], v141 offset:7168
	global_load_lds_dwordx4 v[138:139], off
	v_lshl_add_u64 v[138:139], s[30:31], 0, v[136:137]
	s_add_i32 m0, s44, 0xe000
	s_nop 0
	global_load_lds_dwordx4 v[138:139], off
	s_waitcnt lgkmcnt(8)
	s_barrier
	s_waitcnt lgkmcnt(0)
	s_waitcnt lgkmcnt(0)
	v_mfma_f32_16x16x32_bf16 v[124:127], v[144:147], v[160:163], v[124:127]
	v_mfma_f32_16x16x32_bf16 v[120:123], v[152:155], v[160:163], v[120:123]
	v_mfma_f32_16x16x32_bf16 v[116:119], v[144:147], v[168:171], v[116:119]
	v_mfma_f32_16x16x32_bf16 v[112:115], v[152:155], v[168:171], v[112:115]
	v_mfma_f32_16x16x32_bf16 v[108:111], v[144:147], v[176:179], v[108:111]
	v_mfma_f32_16x16x32_bf16 v[104:107], v[152:155], v[176:179], v[104:107]
	v_mfma_f32_16x16x32_bf16 v[100:103], v[144:147], v[186:189], v[100:103]
	v_mfma_f32_16x16x32_bf16 v[96:99], v[152:155], v[186:189], v[96:99]
	v_mfma_f32_16x16x32_bf16 v[124:127], v[148:151], v[164:167], v[124:127]
	v_mfma_f32_16x16x32_bf16 v[120:123], v[156:159], v[164:167], v[120:123]
	v_mfma_f32_16x16x32_bf16 v[116:119], v[148:151], v[172:175], v[116:119]
	v_mfma_f32_16x16x32_bf16 v[112:115], v[156:159], v[172:175], v[112:115]
	v_mfma_f32_16x16x32_bf16 v[108:111], v[148:151], v[180:183], v[108:111]
	v_mfma_f32_16x16x32_bf16 v[104:107], v[156:159], v[180:183], v[104:107]
	v_mfma_f32_16x16x32_bf16 v[100:103], v[148:151], v[194:197], v[100:103]
	v_mfma_f32_16x16x32_bf16 v[96:99], v[156:159], v[194:197], v[96:99]
	s_barrier
	v_or_b32_e32 v138, 0x14000, v142
	v_add_u32_e32 v139, 0x14400, v142
	ds_read_b128 v[198:201], v138
	ds_read_b128 v[202:205], v139
	v_add_u32_e32 v138, 0x14800, v142
	v_add_u32_e32 v139, 0x14c00, v142
	s_mov_b32 m0, s47
	ds_read_b128 v[206:209], v138
	ds_read_b128 v[210:213], v139
	v_lshl_add_u64 v[138:139], s[36:37], 0, v[184:185]
	global_load_lds_dwordx4 v[138:139], off
	v_lshl_add_u64 v[190:191], s[36:37], 0, v[128:129]
	s_mov_b32 m0, s48
	s_nop 0
	global_load_lds_dwordx4 v[190:191], off
	s_barrier
	s_waitcnt lgkmcnt(0)
	s_waitcnt lgkmcnt(0)
	v_mfma_f32_16x16x32_bf16 v[92:95], v[198:201], v[160:163], v[92:95]
	v_mfma_f32_16x16x32_bf16 v[88:91], v[206:209], v[160:163], v[88:91]
	v_mfma_f32_16x16x32_bf16 v[84:87], v[198:201], v[168:171], v[84:87]
	v_mfma_f32_16x16x32_bf16 v[80:83], v[206:209], v[168:171], v[80:83]
	v_mfma_f32_16x16x32_bf16 v[76:79], v[198:201], v[176:179], v[76:79]
	v_mfma_f32_16x16x32_bf16 v[72:75], v[206:209], v[176:179], v[72:75]
	v_mfma_f32_16x16x32_bf16 v[68:71], v[198:201], v[186:189], v[68:71]
	v_mfma_f32_16x16x32_bf16 v[64:67], v[206:209], v[186:189], v[64:67]
	v_mfma_f32_16x16x32_bf16 v[92:95], v[202:205], v[164:167], v[92:95]
	v_mfma_f32_16x16x32_bf16 v[88:91], v[210:213], v[164:167], v[88:91]
	v_mfma_f32_16x16x32_bf16 v[84:87], v[202:205], v[172:175], v[84:87]
	v_mfma_f32_16x16x32_bf16 v[80:83], v[210:213], v[172:175], v[80:83]
	v_mfma_f32_16x16x32_bf16 v[76:79], v[202:205], v[180:183], v[76:79]
	v_mfma_f32_16x16x32_bf16 v[72:75], v[210:213], v[180:183], v[72:75]
	v_mfma_f32_16x16x32_bf16 v[68:71], v[202:205], v[194:197], v[68:71]
	v_mfma_f32_16x16x32_bf16 v[64:67], v[210:213], v[194:197], v[64:67]
	s_mov_b32 m0, s44
	v_lshl_add_u64 v[214:215], s[34:35], 0, v[132:133]
	s_barrier
	ds_read_b128 v[160:163], v141 offset:16384
	ds_read_b128 v[164:167], v141 offset:17408
	ds_read_b128 v[168:171], v141 offset:18432
	ds_read_b128 v[172:175], v141 offset:19456
	ds_read_b128 v[176:179], v141 offset:20480
	ds_read_b128 v[180:183], v141 offset:21504
	ds_read_b128 v[186:189], v141 offset:22528
	ds_read_b128 v[194:197], v141 offset:23552
	global_load_lds_dwordx4 v[214:215], off
	v_lshl_add_u64 v[216:217], s[34:35], 0, v[130:131]
	s_mov_b32 m0, s49
	s_nop 0
	global_load_lds_dwordx4 v[216:217], off
	s_barrier
	s_waitcnt lgkmcnt(0)
	s_waitcnt lgkmcnt(0)
	s_cbranch_vccnz .Lpjh_s2
	v_mfma_f32_16x16x32_bf16 v[60:63], v[144:147], v[160:163], v[60:63]
	v_mfma_f32_16x16x32_bf16 v[56:59], v[152:155], v[160:163], v[56:59]
	v_mfma_f32_16x16x32_bf16 v[52:55], v[144:147], v[168:171], v[52:55]
	v_mfma_f32_16x16x32_bf16 v[48:51], v[152:155], v[168:171], v[48:51]
	v_mfma_f32_16x16x32_bf16 v[44:47], v[144:147], v[176:179], v[44:47]
	v_mfma_f32_16x16x32_bf16 v[40:43], v[152:155], v[176:179], v[40:43]
	v_mfma_f32_16x16x32_bf16 v[36:39], v[144:147], v[186:189], v[36:39]
	v_mfma_f32_16x16x32_bf16 v[32:35], v[152:155], v[186:189], v[32:35]
	v_mfma_f32_16x16x32_bf16 v[60:63], v[148:151], v[164:167], v[60:63]
	v_mfma_f32_16x16x32_bf16 v[56:59], v[156:159], v[164:167], v[56:59]
	v_mfma_f32_16x16x32_bf16 v[52:55], v[148:151], v[172:175], v[52:55]
	v_mfma_f32_16x16x32_bf16 v[48:51], v[156:159], v[172:175], v[48:51]
	v_mfma_f32_16x16x32_bf16 v[44:47], v[148:151], v[180:183], v[44:47]
	v_mfma_f32_16x16x32_bf16 v[40:43], v[156:159], v[180:183], v[40:43]
	v_mfma_f32_16x16x32_bf16 v[36:39], v[148:151], v[194:197], v[36:39]
	v_mfma_f32_16x16x32_bf16 v[32:35], v[156:159], v[194:197], v[32:35]
.Lpjh_s2:
	s_barrier
	s_add_u32 s36, s36, s88
	s_addc_u32 s37, s37, 0
	s_mov_b32 m0, s50
	v_lshl_add_u64 v[230:231], s[36:37], 0, v[184:185]
	global_load_lds_dwordx4 v[230:231], off
	v_lshl_add_u64 v[232:233], s[36:37], 0, v[128:129]
	s_mov_b32 m0, s51
	s_nop 0
	global_load_lds_dwordx4 v[232:233], off
	s_waitcnt vmcnt(6)
	s_barrier
	s_cbranch_vccnz .Lpjh_s3
	v_mfma_f32_16x16x32_bf16 v[28:31], v[198:201], v[160:163], v[28:31]
	v_mfma_f32_16x16x32_bf16 v[24:27], v[206:209], v[160:163], v[24:27]
	v_mfma_f32_16x16x32_bf16 v[20:23], v[198:201], v[168:171], v[20:23]
	v_mfma_f32_16x16x32_bf16 v[16:19], v[206:209], v[168:171], v[16:19]
	v_mfma_f32_16x16x32_bf16 v[12:15], v[198:201], v[176:179], v[12:15]
	v_mfma_f32_16x16x32_bf16 v[8:11], v[206:209], v[176:179], v[8:11]
	v_mfma_f32_16x16x32_bf16 v[4:7], v[198:201], v[186:189], v[4:7]
	v_mfma_f32_16x16x32_bf16 v[0:3], v[206:209], v[186:189], v[0:3]
	v_mfma_f32_16x16x32_bf16 v[28:31], v[202:205], v[164:167], v[28:31]
	v_mfma_f32_16x16x32_bf16 v[24:27], v[210:213], v[164:167], v[24:27]
	v_mfma_f32_16x16x32_bf16 v[20:23], v[202:205], v[172:175], v[20:23]
	v_mfma_f32_16x16x32_bf16 v[16:19], v[210:213], v[172:175], v[16:19]
	v_mfma_f32_16x16x32_bf16 v[12:15], v[202:205], v[180:183], v[12:15]
	v_mfma_f32_16x16x32_bf16 v[8:11], v[210:213], v[180:183], v[8:11]
	v_mfma_f32_16x16x32_bf16 v[4:7], v[202:205], v[194:197], v[4:7]
	v_mfma_f32_16x16x32_bf16 v[0:3], v[210:213], v[194:197], v[0:3]
.Lpjh_s3:
	v_or_b32_e32 v144, 0x18000, v142
	v_add_u32_e32 v148, 0x18400, v142
	v_add_u32_e32 v152, 0x18800, v142
	v_add_u32_e32 v156, 0x18c00, v142
	s_barrier
	ds_read_b128 v[144:147], v144
	ds_read_b128 v[148:151], v148
	ds_read_b128 v[152:155], v152
	ds_read_b128 v[156:159], v156
	s_add_u32 s34, s34, s88
	s_addc_u32 s35, s35, 0
	s_mov_b32 m0, s52
	v_lshl_add_u64 v[198:199], s[34:35], 0, v[132:133]
	ds_read_b128 v[160:163], v141 offset:32768
	ds_read_b128 v[164:167], v141 offset:33792
	ds_read_b128 v[168:171], v141 offset:34816
	ds_read_b128 v[172:175], v141 offset:35840
	ds_read_b128 v[176:179], v141 offset:36864
	ds_read_b128 v[180:183], v141 offset:37888
	ds_read_b128 v[186:189], v141 offset:38912
	ds_read_b128 v[194:197], v141 offset:39936
	global_load_lds_dwordx4 v[198:199], off
	v_lshl_add_u64 v[198:199], s[34:35], 0, v[130:131]
	s_mov_b32 m0, s53
	s_nop 0
	global_load_lds_dwordx4 v[198:199], off
	s_waitcnt lgkmcnt(8)
	s_barrier
	s_waitcnt lgkmcnt(0)
	s_waitcnt lgkmcnt(0)
	v_mfma_f32_16x16x32_bf16 v[124:127], v[144:147], v[160:163], v[124:127]
	v_mfma_f32_16x16x32_bf16 v[120:123], v[152:155], v[160:163], v[120:123]
	v_mfma_f32_16x16x32_bf16 v[116:119], v[144:147], v[168:171], v[116:119]
	v_mfma_f32_16x16x32_bf16 v[112:115], v[152:155], v[168:171], v[112:115]
	v_mfma_f32_16x16x32_bf16 v[108:111], v[144:147], v[176:179], v[108:111]
	v_mfma_f32_16x16x32_bf16 v[104:107], v[152:155], v[176:179], v[104:107]
	v_mfma_f32_16x16x32_bf16 v[100:103], v[144:147], v[186:189], v[100:103]
	v_mfma_f32_16x16x32_bf16 v[96:99], v[152:155], v[186:189], v[96:99]
	v_mfma_f32_16x16x32_bf16 v[124:127], v[148:151], v[164:167], v[124:127]
	v_mfma_f32_16x16x32_bf16 v[120:123], v[156:159], v[164:167], v[120:123]
	v_mfma_f32_16x16x32_bf16 v[116:119], v[148:151], v[172:175], v[116:119]
	v_mfma_f32_16x16x32_bf16 v[112:115], v[156:159], v[172:175], v[112:115]
	v_mfma_f32_16x16x32_bf16 v[108:111], v[148:151], v[180:183], v[108:111]
	v_mfma_f32_16x16x32_bf16 v[104:107], v[156:159], v[180:183], v[104:107]
	v_mfma_f32_16x16x32_bf16 v[100:103], v[148:151], v[194:197], v[100:103]
	v_mfma_f32_16x16x32_bf16 v[96:99], v[156:159], v[194:197], v[96:99]
	s_barrier
	v_or_b32_e32 v192, 0x1c000, v142
	v_add_u32_e32 v202, 0x1c400, v142
	s_mov_b32 m0, s55
	ds_read_b128 v[198:201], v192
	ds_read_b128 v[202:205], v202
	v_add_u32_e32 v192, 0x1c800, v142
	v_add_u32_e32 v210, 0x1cc00, v142
	v_lshl_add_u64 v[138:139], v[138:139], 0, s[24:25]
	ds_read_b128 v[206:209], v192
	ds_read_b128 v[210:213], v210
	global_load_lds_dwordx4 v[138:139], off
	v_lshl_add_u64 v[138:139], v[190:191], 0, s[24:25]
	s_mov_b32 m0, s58
	s_nop 0
	global_load_lds_dwordx4 v[138:139], off
	s_barrier
	s_waitcnt lgkmcnt(0)
	s_waitcnt lgkmcnt(0)
	v_mfma_f32_16x16x32_bf16 v[92:95], v[198:201], v[160:163], v[92:95]
	v_mfma_f32_16x16x32_bf16 v[88:91], v[206:209], v[160:163], v[88:91]
	v_mfma_f32_16x16x32_bf16 v[84:87], v[198:201], v[168:171], v[84:87]
	v_mfma_f32_16x16x32_bf16 v[80:83], v[206:209], v[168:171], v[80:83]
	v_mfma_f32_16x16x32_bf16 v[76:79], v[198:201], v[176:179], v[76:79]
	v_mfma_f32_16x16x32_bf16 v[72:75], v[206:209], v[176:179], v[72:75]
	v_mfma_f32_16x16x32_bf16 v[68:71], v[198:201], v[186:189], v[68:71]
	v_mfma_f32_16x16x32_bf16 v[64:67], v[206:209], v[186:189], v[64:67]
	v_mfma_f32_16x16x32_bf16 v[92:95], v[202:205], v[164:167], v[92:95]
	v_mfma_f32_16x16x32_bf16 v[88:91], v[210:213], v[164:167], v[88:91]
	v_mfma_f32_16x16x32_bf16 v[84:87], v[202:205], v[172:175], v[84:87]
	v_mfma_f32_16x16x32_bf16 v[80:83], v[210:213], v[172:175], v[80:83]
	v_mfma_f32_16x16x32_bf16 v[76:79], v[202:205], v[180:183], v[76:79]
	v_mfma_f32_16x16x32_bf16 v[72:75], v[210:213], v[180:183], v[72:75]
	v_mfma_f32_16x16x32_bf16 v[68:71], v[202:205], v[194:197], v[68:71]
	v_mfma_f32_16x16x32_bf16 v[64:67], v[210:213], v[194:197], v[64:67]
	s_mov_b32 m0, s59
	v_lshl_add_u64 v[138:139], v[214:215], 0, s[24:25]
	s_barrier
	ds_read_b128 v[160:163], v141 offset:49152
	ds_read_b128 v[164:167], v141 offset:50176
	ds_read_b128 v[168:171], v141 offset:51200
	ds_read_b128 v[172:175], v141 offset:52224
	ds_read_b128 v[176:179], v141 offset:53248
	ds_read_b128 v[180:183], v141 offset:54272
	ds_read_b128 v[186:189], v141 offset:55296
	ds_read_b128 v[194:197], v141 offset:56320
	global_load_lds_dwordx4 v[138:139], off
	v_lshl_add_u64 v[138:139], v[216:217], 0, s[24:25]
	s_mov_b32 m0, s60
	s_nop 0
	global_load_lds_dwordx4 v[138:139], off
	s_barrier
	s_waitcnt lgkmcnt(0)
	s_waitcnt lgkmcnt(0)
	s_cbranch_vccnz .Lpjh_s6
	v_mfma_f32_16x16x32_bf16 v[60:63], v[144:147], v[160:163], v[60:63]
	v_mfma_f32_16x16x32_bf16 v[56:59], v[152:155], v[160:163], v[56:59]
	v_mfma_f32_16x16x32_bf16 v[52:55], v[144:147], v[168:171], v[52:55]
	v_mfma_f32_16x16x32_bf16 v[48:51], v[152:155], v[168:171], v[48:51]
	v_mfma_f32_16x16x32_bf16 v[44:47], v[144:147], v[176:179], v[44:47]
	v_mfma_f32_16x16x32_bf16 v[40:43], v[152:155], v[176:179], v[40:43]
	v_mfma_f32_16x16x32_bf16 v[36:39], v[144:147], v[186:189], v[36:39]
	v_mfma_f32_16x16x32_bf16 v[32:35], v[152:155], v[186:189], v[32:35]
	v_mfma_f32_16x16x32_bf16 v[60:63], v[148:151], v[164:167], v[60:63]
	v_mfma_f32_16x16x32_bf16 v[56:59], v[156:159], v[164:167], v[56:59]
	v_mfma_f32_16x16x32_bf16 v[52:55], v[148:151], v[172:175], v[52:55]
	v_mfma_f32_16x16x32_bf16 v[48:51], v[156:159], v[172:175], v[48:51]
	v_mfma_f32_16x16x32_bf16 v[44:47], v[148:151], v[180:183], v[44:47]
	v_mfma_f32_16x16x32_bf16 v[40:43], v[156:159], v[180:183], v[40:43]
	v_mfma_f32_16x16x32_bf16 v[36:39], v[148:151], v[194:197], v[36:39]
	v_mfma_f32_16x16x32_bf16 v[32:35], v[156:159], v[194:197], v[32:35]
.Lpjh_s6:
	s_barrier
	s_mov_b32 m0, s61
	v_lshl_add_u64 v[138:139], v[230:231], 0, s[24:25]
	global_load_lds_dwordx4 v[138:139], off
	v_lshl_add_u64 v[138:139], v[232:233], 0, s[24:25]
	s_mov_b32 m0, s62
	s_nop 0
	global_load_lds_dwordx4 v[138:139], off
	s_waitcnt vmcnt(6)
	s_barrier
	s_cbranch_vccnz .Lpjh_s7
	v_mfma_f32_16x16x32_bf16 v[28:31], v[198:201], v[160:163], v[28:31]
	v_mfma_f32_16x16x32_bf16 v[24:27], v[206:209], v[160:163], v[24:27]
	v_mfma_f32_16x16x32_bf16 v[20:23], v[198:201], v[168:171], v[20:23]
	v_mfma_f32_16x16x32_bf16 v[16:19], v[206:209], v[168:171], v[16:19]
	v_mfma_f32_16x16x32_bf16 v[12:15], v[198:201], v[176:179], v[12:15]
	v_mfma_f32_16x16x32_bf16 v[8:11], v[206:209], v[176:179], v[8:11]
	v_mfma_f32_16x16x32_bf16 v[4:7], v[198:201], v[186:189], v[4:7]
	v_mfma_f32_16x16x32_bf16 v[0:3], v[206:209], v[186:189], v[0:3]
	v_mfma_f32_16x16x32_bf16 v[28:31], v[202:205], v[164:167], v[28:31]
	v_mfma_f32_16x16x32_bf16 v[24:27], v[210:213], v[164:167], v[24:27]
	v_mfma_f32_16x16x32_bf16 v[20:23], v[202:205], v[172:175], v[20:23]
	v_mfma_f32_16x16x32_bf16 v[16:19], v[210:213], v[172:175], v[16:19]
	v_mfma_f32_16x16x32_bf16 v[12:15], v[202:205], v[180:183], v[12:15]
	v_mfma_f32_16x16x32_bf16 v[8:11], v[210:213], v[180:183], v[8:11]
	v_mfma_f32_16x16x32_bf16 v[4:7], v[202:205], v[194:197], v[4:7]
	v_mfma_f32_16x16x32_bf16 v[0:3], v[210:213], v[194:197], v[0:3]
.Lpjh_s7:
	s_add_u32 s30, s30, 0x100
	s_addc_u32 s31, s31, 0
	s_add_u32 s26, s26, 0x100
	s_addc_u32 s27, s27, 0
	s_cmp_ge_u32 s71, s54
	s_mov_b32 s34, s71
	s_barrier
	s_cbranch_scc0 .LBB0_94
	v_lshl_add_u32 v138, s69, 8, v140
	s_cmp_eq_u32 s100, 2
	s_cselect_b32 vcc_lo, 0x80, 0
	s_nop 0
	v_add_u32_e32 v138, vcc_lo, v138
	v_lshl_or_b32 v144, s70, 8, v143
	v_ashrrev_i32_e32 v139, 31, v138
	v_readlane_b32 s4, v253, 16
	v_ashrrev_i32_e32 v145, 31, v144
	v_cvt_pk_bf16_f32 v124, v124, v125
	v_cvt_pk_bf16_f32 v125, v126, v127
	v_cvt_pk_bf16_f32 v126, v120, v121
	v_lshlrev_b64 v[120:121], 11, v[138:139]
	v_readlane_b32 s5, v253, 17
	v_cvt_pk_bf16_f32 v127, v122, v123
	v_lshlrev_b64 v[122:123], 1, v[144:145]
	v_cvt_pk_bf16_f32 v116, v116, v117
	v_cvt_pk_bf16_f32 v117, v118, v119
	v_cvt_pk_bf16_f32 v119, v114, v115
	s_nop 0
	v_lshl_add_u64 v[120:121], s[4:5], 0, v[120:121]
	v_lshl_add_u64 v[120:121], v[120:121], 0, v[122:123]
	global_store_dwordx4 v[120:121], v[124:127], off
	v_or_b32_e32 v114, 32, v138
	v_cvt_pk_bf16_f32 v108, v108, v109
	v_cvt_pk_bf16_f32 v109, v110, v111
	v_cvt_pk_bf16_f32 v111, v106, v107
	v_or_b32_e32 v106, 48, v138
	v_or_b32_e32 v124, 16, v138
	v_cvt_pk_bf16_f32 v68, v68, v69
	v_cvt_pk_bf16_f32 v69, v70, v71
	v_cvt_pk_bf16_f32 v70, v64, v65
	v_add_u32_e32 v64, 0x80, v138
	v_cvt_pk_bf16_f32 v60, v60, v61
	v_cvt_pk_bf16_f32 v61, v62, v63
	v_cvt_pk_bf16_f32 v63, v58, v59
	v_add_u32_e32 v58, 0x90, v138
	v_cvt_pk_bf16_f32 v52, v52, v53
	v_cvt_pk_bf16_f32 v53, v54, v55
	v_cvt_pk_bf16_f32 v55, v50, v51
	v_add_u32_e32 v50, 0xa0, v138
	v_cvt_pk_bf16_f32 v44, v44, v45
	v_cvt_pk_bf16_f32 v45, v46, v47
	v_cvt_pk_bf16_f32 v47, v42, v43
	v_add_u32_e32 v42, 0xb0, v138
	v_ashrrev_i32_e32 v125, 31, v124
	v_ashrrev_i32_e32 v115, 31, v114
	v_ashrrev_i32_e32 v107, 31, v106
	v_ashrrev_i32_e32 v65, 31, v64
	v_ashrrev_i32_e32 v59, 31, v58
	v_ashrrev_i32_e32 v51, 31, v50
	v_ashrrev_i32_e32 v43, 31, v42
	v_cvt_pk_bf16_f32 v118, v112, v113
	v_lshlrev_b64 v[112:113], 11, v[124:125]
	v_cvt_pk_bf16_f32 v110, v104, v105
	v_lshlrev_b64 v[104:105], 11, v[114:115]
	v_cvt_pk_bf16_f32 v100, v100, v101
	v_cvt_pk_bf16_f32 v101, v102, v103
	v_cvt_pk_bf16_f32 v102, v96, v97
	v_lshlrev_b64 v[96:97], 11, v[106:107]
	v_cvt_pk_bf16_f32 v62, v56, v57
	v_lshlrev_b64 v[56:57], 11, v[64:65]
	v_cvt_pk_bf16_f32 v54, v48, v49
	v_lshlrev_b64 v[48:49], 11, v[58:59]
	v_cvt_pk_bf16_f32 v46, v40, v41
	v_lshlrev_b64 v[40:41], 11, v[50:51]
	v_cvt_pk_bf16_f32 v36, v36, v37
	v_cvt_pk_bf16_f32 v37, v38, v39
	v_cvt_pk_bf16_f32 v38, v32, v33
	v_lshlrev_b64 v[32:33], 11, v[42:43]
	v_lshl_add_u64 v[112:113], s[4:5], 0, v[112:113]
	v_lshl_add_u64 v[104:105], s[4:5], 0, v[104:105]
	v_lshl_add_u64 v[96:97], s[4:5], 0, v[96:97]
	v_lshl_add_u64 v[56:57], s[4:5], 0, v[56:57]
	v_lshl_add_u64 v[48:49], s[4:5], 0, v[48:49]
	v_lshl_add_u64 v[40:41], s[4:5], 0, v[40:41]
	v_lshl_add_u64 v[32:33], s[4:5], 0, v[32:33]
	v_lshl_add_u64 v[112:113], v[112:113], 0, v[122:123]
	v_lshl_add_u64 v[104:105], v[104:105], 0, v[122:123]
	v_lshl_add_u64 v[96:97], v[96:97], 0, v[122:123]
	v_lshl_add_u64 v[56:57], v[56:57], 0, v[122:123]
	v_lshl_add_u64 v[48:49], v[48:49], 0, v[122:123]
	v_lshl_add_u64 v[40:41], v[40:41], 0, v[122:123]
	v_lshl_add_u64 v[32:33], v[32:33], 0, v[122:123]
	s_and_b64 vcc, exec, s[22:23]
	s_mov_b32 s70, s65
	s_mov_b32 s69, s68
	s_mov_b64 s[34:35], s[0:1]
	s_mov_b64 s[30:31], s[28:29]
	s_mov_b32 s71, 0x42ce8ed0
	v_readlane_b32 s6, v253, 18
	v_readlane_b32 s7, v253, 19
	v_readlane_b32 s8, v253, 20
	v_readlane_b32 s9, v253, 21
	v_readlane_b32 s10, v253, 22
	v_readlane_b32 s11, v253, 23
	v_readlane_b32 s12, v253, 24
	v_readlane_b32 s13, v253, 25
	v_readlane_b32 s14, v253, 26
	v_readlane_b32 s15, v253, 27
	v_readlane_b32 s16, v253, 28
	v_readlane_b32 s17, v253, 29
	v_readlane_b32 s18, v253, 30
	v_readlane_b32 s19, v253, 31
	global_store_dwordx4 v[112:113], v[116:119], off
	global_store_dwordx4 v[104:105], v[108:111], off
	v_cvt_pk_bf16_f32 v103, v98, v99
	global_store_dwordx4 v[96:97], v[100:103], off
	v_cvt_pk_bf16_f32 v92, v92, v93
	v_cvt_pk_bf16_f32 v93, v94, v95
	v_cvt_pk_bf16_f32 v94, v88, v89
	v_cvt_pk_bf16_f32 v95, v90, v91
	global_store_dwordx4 v[120:121], v[92:95], off offset:256
	v_cvt_pk_bf16_f32 v84, v84, v85
	v_cvt_pk_bf16_f32 v85, v86, v87
	v_cvt_pk_bf16_f32 v86, v80, v81
	v_cvt_pk_bf16_f32 v87, v82, v83
	global_store_dwordx4 v[112:113], v[84:87], off offset:256
	v_cvt_pk_bf16_f32 v76, v76, v77
	v_cvt_pk_bf16_f32 v77, v78, v79
	v_cvt_pk_bf16_f32 v78, v72, v73
	v_cvt_pk_bf16_f32 v79, v74, v75
	global_store_dwordx4 v[104:105], v[76:79], off offset:256
	v_cvt_pk_bf16_f32 v71, v66, v67
	global_store_dwordx4 v[96:97], v[68:71], off offset:256
	s_cmp_lg_u32 s100, 0
	s_cbranch_scc1 .Lpjh_nost
	global_store_dwordx4 v[56:57], v[60:63], off
	global_store_dwordx4 v[48:49], v[52:55], off
	global_store_dwordx4 v[40:41], v[44:47], off
	v_cvt_pk_bf16_f32 v39, v34, v35
	global_store_dwordx4 v[32:33], v[36:39], off
	v_cvt_pk_bf16_f32 v28, v28, v29
	v_cvt_pk_bf16_f32 v29, v30, v31
	v_cvt_pk_bf16_f32 v30, v24, v25
	v_cvt_pk_bf16_f32 v31, v26, v27
	global_store_dwordx4 v[56:57], v[28:31], off offset:256
	v_cvt_pk_bf16_f32 v20, v20, v21
	v_cvt_pk_bf16_f32 v21, v22, v23
	v_cvt_pk_bf16_f32 v22, v16, v17
	v_cvt_pk_bf16_f32 v23, v18, v19
	global_store_dwordx4 v[48:49], v[20:23], off offset:256
	v_cvt_pk_bf16_f32 v12, v12, v13
	v_cvt_pk_bf16_f32 v13, v14, v15
	v_cvt_pk_bf16_f32 v14, v8, v9
	v_cvt_pk_bf16_f32 v15, v10, v11
	global_store_dwordx4 v[40:41], v[12:15], off offset:256
	v_cvt_pk_bf16_f32 v4, v4, v5
	v_cvt_pk_bf16_f32 v5, v6, v7
	v_cvt_pk_bf16_f32 v6, v0, v1
	v_cvt_pk_bf16_f32 v7, v2, v3
	global_store_dwordx4 v[32:33], v[4:7], off offset:256

.LBB0_112:
	v_or_b32_e32 v100, 0x10000, v244
	v_add_u32_e32 v104, 0x10400, v244
	v_add_u32_e32 v116, 0x10800, v244
	v_add_u32_e32 v120, 0x10c00, v244
	s_add_i32 s45, s28, 2
	ds_read_b128 v[100:103], v100
	ds_read_b128 v[104:107], v104
	ds_read_b128 v[116:119], v116
	ds_read_b128 v[120:123], v120
	s_add_u32 s29, s22, 0xfffc0080
	s_addc_u32 s30, s23, -1
	s_cmp_eq_u32 s68, s28
	s_cselect_b32 s28, s37, s38
	s_cselect_b32 s31, s27, s30
	s_cselect_b32 s30, s33, s29
	s_cselect_b32 s29, s36, s39
	v_lshl_add_u64 v[176:177], s[22:23], 0, v[194:195]
	s_add_i32 m0, s59, 0xc000
	ds_read_b128 v[132:135], v243
	ds_read_b128 v[140:143], v243 offset:1024
	ds_read_b128 v[152:155], v243 offset:2048
	ds_read_b128 v[156:159], v243 offset:3072
	ds_read_b128 v[160:163], v243 offset:4096
	ds_read_b128 v[164:167], v243 offset:5120
	ds_read_b128 v[168:171], v243 offset:6144
	ds_read_b128 v[172:175], v243 offset:7168
	global_load_lds_dwordx4 v[176:177], off
	v_lshl_add_u64 v[176:177], s[22:23], 0, v[196:197]
	s_add_i32 m0, s59, 0xe000
	s_nop 0
	global_load_lds_dwordx4 v[176:177], off
	s_waitcnt lgkmcnt(8)
	s_barrier
	s_waitcnt lgkmcnt(0)
	s_waitcnt lgkmcnt(0)
	v_mfma_f32_16x16x32_bf16 v[148:151], v[100:103], v[132:135], v[148:151]
	v_mfma_f32_16x16x32_bf16 v[144:147], v[116:119], v[132:135], v[144:147]
	v_mfma_f32_16x16x32_bf16 v[136:139], v[100:103], v[152:155], v[136:139]
	v_mfma_f32_16x16x32_bf16 v[128:131], v[116:119], v[152:155], v[128:131]
	v_mfma_f32_16x16x32_bf16 v[124:127], v[100:103], v[160:163], v[124:127]
	v_mfma_f32_16x16x32_bf16 v[112:115], v[116:119], v[160:163], v[112:115]
	v_mfma_f32_16x16x32_bf16 v[108:111], v[100:103], v[168:171], v[108:111]
	v_mfma_f32_16x16x32_bf16 v[96:99], v[116:119], v[168:171], v[96:99]
	v_mfma_f32_16x16x32_bf16 v[148:151], v[104:107], v[140:143], v[148:151]
	v_mfma_f32_16x16x32_bf16 v[144:147], v[120:123], v[140:143], v[144:147]
	v_mfma_f32_16x16x32_bf16 v[136:139], v[104:107], v[156:159], v[136:139]
	v_mfma_f32_16x16x32_bf16 v[128:131], v[120:123], v[156:159], v[128:131]
	v_mfma_f32_16x16x32_bf16 v[124:127], v[104:107], v[164:167], v[124:127]
	v_mfma_f32_16x16x32_bf16 v[112:115], v[120:123], v[164:167], v[112:115]
	v_mfma_f32_16x16x32_bf16 v[108:111], v[104:107], v[172:175], v[108:111]
	v_mfma_f32_16x16x32_bf16 v[96:99], v[120:123], v[172:175], v[96:99]
	s_barrier
	s_mov_b32 m0, s53
	v_or_b32_e32 v176, 0x14000, v244
	v_add_u32_e32 v180, 0x14400, v244
	v_add_u32_e32 v198, 0x14800, v244
	v_add_u32_e32 v202, 0x14c00, v244
	v_lshl_add_u64 v[206:207], s[28:29], 0, v[184:185]
	ds_read_b128 v[176:179], v176
	ds_read_b128 v[180:183], v180
	ds_read_b128 v[198:201], v198
	ds_read_b128 v[202:205], v202
	global_load_lds_dwordx4 v[206:207], off
	v_lshl_add_u64 v[208:209], s[28:29], 0, v[190:191]
	s_mov_b32 m0, s60
	s_nop 0
	global_load_lds_dwordx4 v[208:209], off
	s_barrier
	s_waitcnt lgkmcnt(0)
	s_waitcnt lgkmcnt(0)
	v_mfma_f32_16x16x32_bf16 v[92:95], v[176:179], v[132:135], v[92:95]
	v_mfma_f32_16x16x32_bf16 v[88:91], v[198:201], v[132:135], v[88:91]
	v_mfma_f32_16x16x32_bf16 v[84:87], v[176:179], v[152:155], v[84:87]
	v_mfma_f32_16x16x32_bf16 v[80:83], v[198:201], v[152:155], v[80:83]
	v_mfma_f32_16x16x32_bf16 v[76:79], v[176:179], v[160:163], v[76:79]
	v_mfma_f32_16x16x32_bf16 v[72:75], v[198:201], v[160:163], v[72:75]
	v_mfma_f32_16x16x32_bf16 v[68:71], v[176:179], v[168:171], v[68:71]
	v_mfma_f32_16x16x32_bf16 v[64:67], v[198:201], v[168:171], v[64:67]
	v_mfma_f32_16x16x32_bf16 v[92:95], v[180:183], v[140:143], v[92:95]
	v_mfma_f32_16x16x32_bf16 v[88:91], v[202:205], v[140:143], v[88:91]
	v_mfma_f32_16x16x32_bf16 v[84:87], v[180:183], v[156:159], v[84:87]
	v_mfma_f32_16x16x32_bf16 v[80:83], v[202:205], v[156:159], v[80:83]
	v_mfma_f32_16x16x32_bf16 v[76:79], v[180:183], v[164:167], v[76:79]
	v_mfma_f32_16x16x32_bf16 v[72:75], v[202:205], v[164:167], v[72:75]
	v_mfma_f32_16x16x32_bf16 v[68:71], v[180:183], v[172:175], v[68:71]
	v_mfma_f32_16x16x32_bf16 v[64:67], v[202:205], v[172:175], v[64:67]
	s_mov_b32 m0, s59
	v_lshl_add_u64 v[210:211], s[30:31], 0, v[186:187]
	s_barrier
	ds_read_b128 v[132:135], v243 offset:16384
	ds_read_b128 v[140:143], v243 offset:17408
	ds_read_b128 v[152:155], v243 offset:18432
	ds_read_b128 v[156:159], v243 offset:19456
	ds_read_b128 v[160:163], v243 offset:20480
	ds_read_b128 v[164:167], v243 offset:21504
	ds_read_b128 v[168:171], v243 offset:22528
	ds_read_b128 v[172:175], v243 offset:23552
	global_load_lds_dwordx4 v[210:211], off
	v_lshl_add_u64 v[212:213], s[30:31], 0, v[188:189]
	s_mov_b32 m0, s61
	s_nop 0
	global_load_lds_dwordx4 v[212:213], off
	s_barrier
	s_waitcnt lgkmcnt(0)
	s_waitcnt lgkmcnt(0)
	v_mfma_f32_16x16x32_bf16 v[60:63], v[100:103], v[132:135], v[60:63]
	v_mfma_f32_16x16x32_bf16 v[56:59], v[116:119], v[132:135], v[56:59]
	v_mfma_f32_16x16x32_bf16 v[52:55], v[100:103], v[152:155], v[52:55]
	v_mfma_f32_16x16x32_bf16 v[48:51], v[116:119], v[152:155], v[48:51]
	v_mfma_f32_16x16x32_bf16 v[44:47], v[100:103], v[160:163], v[44:47]
	v_mfma_f32_16x16x32_bf16 v[40:43], v[116:119], v[160:163], v[40:43]
	v_mfma_f32_16x16x32_bf16 v[36:39], v[100:103], v[168:171], v[36:39]
	v_mfma_f32_16x16x32_bf16 v[32:35], v[116:119], v[168:171], v[32:35]
	v_mfma_f32_16x16x32_bf16 v[60:63], v[104:107], v[140:143], v[60:63]
	v_mfma_f32_16x16x32_bf16 v[56:59], v[120:123], v[140:143], v[56:59]
	v_mfma_f32_16x16x32_bf16 v[52:55], v[104:107], v[156:159], v[52:55]
	v_mfma_f32_16x16x32_bf16 v[48:51], v[120:123], v[156:159], v[48:51]
	v_mfma_f32_16x16x32_bf16 v[44:47], v[104:107], v[164:167], v[44:47]
	v_mfma_f32_16x16x32_bf16 v[40:43], v[120:123], v[164:167], v[40:43]
	v_mfma_f32_16x16x32_bf16 v[36:39], v[104:107], v[172:175], v[36:39]
	v_mfma_f32_16x16x32_bf16 v[32:35], v[120:123], v[172:175], v[32:35]
	s_barrier
	s_add_u32 s66, s28, 0x10000
	s_addc_u32 s67, s29, 0
	s_mov_b32 m0, s62
	v_lshl_add_u64 v[100:101], s[66:67], 0, v[184:185]
	global_load_lds_dwordx4 v[100:101], off
	v_lshl_add_u64 v[100:101], s[66:67], 0, v[190:191]
	s_mov_b32 m0, s63
	s_nop 0
	global_load_lds_dwordx4 v[100:101], off
	s_waitcnt vmcnt(6)
	s_barrier
	v_mfma_f32_16x16x32_bf16 v[28:31], v[176:179], v[132:135], v[28:31]
	v_mfma_f32_16x16x32_bf16 v[24:27], v[198:201], v[132:135], v[24:27]
	v_mfma_f32_16x16x32_bf16 v[20:23], v[176:179], v[152:155], v[20:23]
	v_mfma_f32_16x16x32_bf16 v[16:19], v[198:201], v[152:155], v[16:19]
	v_mfma_f32_16x16x32_bf16 v[12:15], v[176:179], v[160:163], v[12:15]
	v_mfma_f32_16x16x32_bf16 v[4:7], v[198:201], v[160:163], v[4:7]
	v_mfma_f32_16x16x32_bf16 v[8:11], v[176:179], v[168:171], v[8:11]
	v_mfma_f32_16x16x32_bf16 v[0:3], v[198:201], v[168:171], v[0:3]
	v_mfma_f32_16x16x32_bf16 v[28:31], v[180:183], v[140:143], v[28:31]
	v_mfma_f32_16x16x32_bf16 v[24:27], v[202:205], v[140:143], v[24:27]
	v_mfma_f32_16x16x32_bf16 v[20:23], v[180:183], v[156:159], v[20:23]
	v_mfma_f32_16x16x32_bf16 v[16:19], v[202:205], v[156:159], v[16:19]
	v_mfma_f32_16x16x32_bf16 v[12:15], v[180:183], v[164:167], v[12:15]
	v_mfma_f32_16x16x32_bf16 v[4:7], v[202:205], v[164:167], v[4:7]
	v_mfma_f32_16x16x32_bf16 v[8:11], v[180:183], v[172:175], v[8:11]
	v_mfma_f32_16x16x32_bf16 v[0:3], v[202:205], v[172:175], v[0:3]
	v_or_b32_e32 v100, 0x18000, v244
	v_add_u32_e32 v104, 0x18400, v244
	v_add_u32_e32 v116, 0x18800, v244
	v_add_u32_e32 v120, 0x18c00, v244
	s_barrier
	ds_read_b128 v[100:103], v100
	ds_read_b128 v[104:107], v104
	ds_read_b128 v[116:119], v116
	ds_read_b128 v[120:123], v120
	s_add_u32 s30, s30, 0x40000
	s_addc_u32 s31, s31, 0
	s_mov_b32 m0, s64
	v_lshl_add_u64 v[176:177], s[30:31], 0, v[186:187]
	ds_read_b128 v[132:135], v243 offset:32768
	ds_read_b128 v[140:143], v243 offset:33792
	ds_read_b128 v[152:155], v243 offset:34816
	ds_read_b128 v[156:159], v243 offset:35840
	ds_read_b128 v[160:163], v243 offset:36864
	ds_read_b128 v[164:167], v243 offset:37888
	ds_read_b128 v[168:171], v243 offset:38912
	ds_read_b128 v[172:175], v243 offset:39936
	global_load_lds_dwordx4 v[176:177], off
	v_lshl_add_u64 v[176:177], s[30:31], 0, v[188:189]
	s_mov_b32 m0, s65
	s_nop 0
	global_load_lds_dwordx4 v[176:177], off
	s_waitcnt lgkmcnt(8)
	s_barrier
	s_waitcnt lgkmcnt(0)
	s_waitcnt lgkmcnt(0)
	v_mfma_f32_16x16x32_bf16 v[148:151], v[100:103], v[132:135], v[148:151]
	v_mfma_f32_16x16x32_bf16 v[144:147], v[116:119], v[132:135], v[144:147]
	v_mfma_f32_16x16x32_bf16 v[136:139], v[100:103], v[152:155], v[136:139]
	v_mfma_f32_16x16x32_bf16 v[128:131], v[116:119], v[152:155], v[128:131]
	v_mfma_f32_16x16x32_bf16 v[124:127], v[100:103], v[160:163], v[124:127]
	v_mfma_f32_16x16x32_bf16 v[112:115], v[116:119], v[160:163], v[112:115]
	v_mfma_f32_16x16x32_bf16 v[108:111], v[100:103], v[168:171], v[108:111]
	v_mfma_f32_16x16x32_bf16 v[96:99], v[116:119], v[168:171], v[96:99]
	v_mfma_f32_16x16x32_bf16 v[148:151], v[104:107], v[140:143], v[148:151]
	v_mfma_f32_16x16x32_bf16 v[144:147], v[120:123], v[140:143], v[144:147]
	v_mfma_f32_16x16x32_bf16 v[136:139], v[104:107], v[156:159], v[136:139]
	v_mfma_f32_16x16x32_bf16 v[128:131], v[120:123], v[156:159], v[128:131]
	v_mfma_f32_16x16x32_bf16 v[124:127], v[104:107], v[164:167], v[124:127]
	v_mfma_f32_16x16x32_bf16 v[112:115], v[120:123], v[164:167], v[112:115]
	v_mfma_f32_16x16x32_bf16 v[108:111], v[104:107], v[172:175], v[108:111]
	v_mfma_f32_16x16x32_bf16 v[96:99], v[120:123], v[172:175], v[96:99]
	s_barrier
	s_mov_b32 m0, s69
	v_or_b32_e32 v176, 0x1c000, v244
	v_add_u32_e32 v180, 0x1c400, v244
	v_add_u32_e32 v198, 0x1c800, v244
	v_add_u32_e32 v202, 0x1cc00, v244
	v_lshl_add_u64 v[206:207], v[206:207], 0, s[24:25]
	ds_read_b128 v[176:179], v176
	ds_read_b128 v[180:183], v180
	ds_read_b128 v[198:201], v198
	ds_read_b128 v[202:205], v202
	global_load_lds_dwordx4 v[206:207], off
	v_lshl_add_u64 v[206:207], v[208:209], 0, s[24:25]
	s_mov_b32 m0, s70
	s_nop 0
	global_load_lds_dwordx4 v[206:207], off
	s_barrier
	s_waitcnt lgkmcnt(0)
	s_waitcnt lgkmcnt(0)
	v_mfma_f32_16x16x32_bf16 v[92:95], v[176:179], v[132:135], v[92:95]
	v_mfma_f32_16x16x32_bf16 v[88:91], v[198:201], v[132:135], v[88:91]
	v_mfma_f32_16x16x32_bf16 v[84:87], v[176:179], v[152:155], v[84:87]
	v_mfma_f32_16x16x32_bf16 v[80:83], v[198:201], v[152:155], v[80:83]
	v_mfma_f32_16x16x32_bf16 v[76:79], v[176:179], v[160:163], v[76:79]
	v_mfma_f32_16x16x32_bf16 v[72:75], v[198:201], v[160:163], v[72:75]
	v_mfma_f32_16x16x32_bf16 v[68:71], v[176:179], v[168:171], v[68:71]
	v_mfma_f32_16x16x32_bf16 v[64:67], v[198:201], v[168:171], v[64:67]
	v_mfma_f32_16x16x32_bf16 v[92:95], v[180:183], v[140:143], v[92:95]
	v_mfma_f32_16x16x32_bf16 v[88:91], v[202:205], v[140:143], v[88:91]
	v_mfma_f32_16x16x32_bf16 v[84:87], v[180:183], v[156:159], v[84:87]
	v_mfma_f32_16x16x32_bf16 v[80:83], v[202:205], v[156:159], v[80:83]
	v_mfma_f32_16x16x32_bf16 v[76:79], v[180:183], v[164:167], v[76:79]
	v_mfma_f32_16x16x32_bf16 v[72:75], v[202:205], v[164:167], v[72:75]
	v_mfma_f32_16x16x32_bf16 v[68:71], v[180:183], v[172:175], v[68:71]
	v_mfma_f32_16x16x32_bf16 v[64:67], v[202:205], v[172:175], v[64:67]
	s_mov_b32 m0, s71
	v_lshl_add_u64 v[206:207], v[210:211], 0, s[24:25]
	s_barrier
	ds_read_b128 v[132:135], v243 offset:49152
	ds_read_b128 v[140:143], v243 offset:50176
	ds_read_b128 v[152:155], v243 offset:51200
	ds_read_b128 v[156:159], v243 offset:52224
	ds_read_b128 v[160:163], v243 offset:53248
	ds_read_b128 v[164:167], v243 offset:54272
	ds_read_b128 v[168:171], v243 offset:55296
	ds_read_b128 v[172:175], v243 offset:56320
	global_load_lds_dwordx4 v[206:207], off
	v_lshl_add_u64 v[206:207], v[212:213], 0, s[24:25]
	s_mov_b32 m0, s54
	s_nop 0
	global_load_lds_dwordx4 v[206:207], off
	s_barrier
	s_waitcnt lgkmcnt(0)
	s_waitcnt lgkmcnt(0)
	v_mfma_f32_16x16x32_bf16 v[60:63], v[100:103], v[132:135], v[60:63]
	v_mfma_f32_16x16x32_bf16 v[56:59], v[116:119], v[132:135], v[56:59]
	v_mfma_f32_16x16x32_bf16 v[52:55], v[100:103], v[152:155], v[52:55]
	v_mfma_f32_16x16x32_bf16 v[48:51], v[116:119], v[152:155], v[48:51]
	v_mfma_f32_16x16x32_bf16 v[44:47], v[100:103], v[160:163], v[44:47]
	v_mfma_f32_16x16x32_bf16 v[40:43], v[116:119], v[160:163], v[40:43]
	v_mfma_f32_16x16x32_bf16 v[36:39], v[100:103], v[168:171], v[36:39]
	v_mfma_f32_16x16x32_bf16 v[32:35], v[116:119], v[168:171], v[32:35]
	v_mfma_f32_16x16x32_bf16 v[60:63], v[104:107], v[140:143], v[60:63]
	v_mfma_f32_16x16x32_bf16 v[56:59], v[120:123], v[140:143], v[56:59]
	v_mfma_f32_16x16x32_bf16 v[52:55], v[104:107], v[156:159], v[52:55]
	v_mfma_f32_16x16x32_bf16 v[48:51], v[120:123], v[156:159], v[48:51]
	v_mfma_f32_16x16x32_bf16 v[44:47], v[104:107], v[164:167], v[44:47]
	v_mfma_f32_16x16x32_bf16 v[40:43], v[120:123], v[164:167], v[40:43]
	v_mfma_f32_16x16x32_bf16 v[36:39], v[104:107], v[172:175], v[36:39]
	v_mfma_f32_16x16x32_bf16 v[32:35], v[120:123], v[172:175], v[32:35]
	s_barrier
	s_add_u32 s28, s28, 0x10080
	s_addc_u32 s29, s29, 0
	s_mov_b32 m0, s40
	v_lshl_add_u64 v[100:101], s[28:29], 0, v[184:185]
	global_load_lds_dwordx4 v[100:101], off
	v_lshl_add_u64 v[100:101], s[28:29], 0, v[190:191]
	s_mov_b32 m0, s41
	s_nop 0
	global_load_lds_dwordx4 v[100:101], off
	s_waitcnt vmcnt(6)
	s_barrier
	v_mfma_f32_16x16x32_bf16 v[28:31], v[176:179], v[132:135], v[28:31]
	v_mfma_f32_16x16x32_bf16 v[24:27], v[198:201], v[132:135], v[24:27]
	v_mfma_f32_16x16x32_bf16 v[20:23], v[176:179], v[152:155], v[20:23]
	v_mfma_f32_16x16x32_bf16 v[16:19], v[198:201], v[152:155], v[16:19]
	v_mfma_f32_16x16x32_bf16 v[12:15], v[176:179], v[160:163], v[12:15]
	v_mfma_f32_16x16x32_bf16 v[4:7], v[198:201], v[160:163], v[4:7]
	v_mfma_f32_16x16x32_bf16 v[8:11], v[176:179], v[168:171], v[8:11]
	v_mfma_f32_16x16x32_bf16 v[0:3], v[198:201], v[168:171], v[0:3]
	v_mfma_f32_16x16x32_bf16 v[28:31], v[180:183], v[140:143], v[28:31]
	v_mfma_f32_16x16x32_bf16 v[24:27], v[202:205], v[140:143], v[24:27]
	v_mfma_f32_16x16x32_bf16 v[20:23], v[180:183], v[156:159], v[20:23]
	v_mfma_f32_16x16x32_bf16 v[16:19], v[202:205], v[156:159], v[16:19]
	v_mfma_f32_16x16x32_bf16 v[12:15], v[180:183], v[164:167], v[12:15]
	v_mfma_f32_16x16x32_bf16 v[4:7], v[202:205], v[164:167], v[4:7]
	v_mfma_f32_16x16x32_bf16 v[8:11], v[180:183], v[172:175], v[8:11]
	v_mfma_f32_16x16x32_bf16 v[0:3], v[202:205], v[172:175], v[0:3]
	s_add_u32 s22, s22, 0x100
	s_addc_u32 s23, s23, 0
	s_add_u32 s38, s38, 0x100
	s_addc_u32 s39, s39, 0
	s_cmp_ge_i32 s45, s34
	s_mov_b32 s28, s45
	s_barrier
	s_cbranch_scc0 .LBB0_112
	s_mov_b32 s66, s4
	s_mov_b32 s67, s5

.LBB0_234:
	v_or_b32_e32 v141, 0x10000, v143
	v_add_u32_e32 v148, 0x10400, v143
	ds_read_b128 v[144:147], v141
	ds_read_b128 v[148:151], v148
	v_add_u32_e32 v141, 0x10800, v143
	v_add_u32_e32 v156, 0x10c00, v143
	ds_read_b128 v[152:155], v141
	ds_read_b128 v[156:159], v156
	s_add_u32 s34, s30, 0xfff00080
	s_addc_u32 s35, s31, -1
	s_cmp_eq_u32 s96, 12
	s_cselect_b32 s37, vcc_lo, s35
	s_cselect_b32 s36, vcc_hi, s34
	s_cselect_b32 s35, s33, s27
	s_cselect_b32 s34, s20, s26
	v_lshl_add_u64 v[190:191], s[30:31], 0, v[136:137]
	s_add_i32 m0, s38, 0xc000
	ds_read_b128 v[160:163], v142
	ds_read_b128 v[164:167], v142 offset:1024
	ds_read_b128 v[168:171], v142 offset:2048
	ds_read_b128 v[172:175], v142 offset:3072
	ds_read_b128 v[176:179], v142 offset:4096
	ds_read_b128 v[180:183], v142 offset:5120
	ds_read_b128 v[186:189], v142 offset:6144
	ds_read_b128 v[194:197], v142 offset:7168
	global_load_lds_dwordx4 v[190:191], off
	v_lshl_add_u64 v[190:191], s[30:31], 0, v[138:139]
	s_add_i32 m0, s38, 0xe000
	s_nop 0
	global_load_lds_dwordx4 v[190:191], off
	s_waitcnt lgkmcnt(8)
	s_barrier
	s_waitcnt lgkmcnt(0)
	s_waitcnt lgkmcnt(0)
	v_mfma_f32_16x16x32_bf16 v[124:127], v[144:147], v[160:163], v[124:127]
	v_mfma_f32_16x16x32_bf16 v[120:123], v[152:155], v[160:163], v[120:123]
	v_mfma_f32_16x16x32_bf16 v[116:119], v[144:147], v[168:171], v[116:119]
	v_mfma_f32_16x16x32_bf16 v[112:115], v[152:155], v[168:171], v[112:115]
	v_mfma_f32_16x16x32_bf16 v[108:111], v[144:147], v[176:179], v[108:111]
	v_mfma_f32_16x16x32_bf16 v[104:107], v[152:155], v[176:179], v[104:107]
	v_mfma_f32_16x16x32_bf16 v[100:103], v[144:147], v[186:189], v[100:103]
	v_mfma_f32_16x16x32_bf16 v[96:99], v[152:155], v[186:189], v[96:99]
	v_mfma_f32_16x16x32_bf16 v[124:127], v[148:151], v[164:167], v[124:127]
	v_mfma_f32_16x16x32_bf16 v[120:123], v[156:159], v[164:167], v[120:123]
	v_mfma_f32_16x16x32_bf16 v[116:119], v[148:151], v[172:175], v[116:119]
	v_mfma_f32_16x16x32_bf16 v[112:115], v[156:159], v[172:175], v[112:115]
	v_mfma_f32_16x16x32_bf16 v[108:111], v[148:151], v[180:183], v[108:111]
	v_mfma_f32_16x16x32_bf16 v[104:107], v[156:159], v[180:183], v[104:107]
	v_mfma_f32_16x16x32_bf16 v[100:103], v[148:151], v[194:197], v[100:103]
	v_mfma_f32_16x16x32_bf16 v[96:99], v[156:159], v[194:197], v[96:99]
	s_barrier
	v_or_b32_e32 v141, 0x14000, v143
	v_add_u32_e32 v190, 0x14400, v143
	ds_read_b128 v[198:201], v141
	ds_read_b128 v[202:205], v190
	v_add_u32_e32 v141, 0x14800, v143
	v_add_u32_e32 v190, 0x14c00, v143
	s_mov_b32 m0, s39
	ds_read_b128 v[206:209], v141
	ds_read_b128 v[210:213], v190
	v_lshl_add_u64 v[190:191], s[34:35], 0, v[132:133]
	global_load_lds_dwordx4 v[190:191], off
	v_lshl_add_u64 v[214:215], s[34:35], 0, v[128:129]
	s_mov_b32 m0, s40
	s_nop 0
	global_load_lds_dwordx4 v[214:215], off
	s_barrier
	s_waitcnt lgkmcnt(0)
	s_waitcnt lgkmcnt(0)
	v_mfma_f32_16x16x32_bf16 v[92:95], v[198:201], v[160:163], v[92:95]
	v_mfma_f32_16x16x32_bf16 v[88:91], v[206:209], v[160:163], v[88:91]
	v_mfma_f32_16x16x32_bf16 v[84:87], v[198:201], v[168:171], v[84:87]
	v_mfma_f32_16x16x32_bf16 v[80:83], v[206:209], v[168:171], v[80:83]
	v_mfma_f32_16x16x32_bf16 v[76:79], v[198:201], v[176:179], v[76:79]
	v_mfma_f32_16x16x32_bf16 v[72:75], v[206:209], v[176:179], v[72:75]
	v_mfma_f32_16x16x32_bf16 v[68:71], v[198:201], v[186:189], v[68:71]
	v_mfma_f32_16x16x32_bf16 v[64:67], v[206:209], v[186:189], v[64:67]
	v_mfma_f32_16x16x32_bf16 v[92:95], v[202:205], v[164:167], v[92:95]
	v_mfma_f32_16x16x32_bf16 v[88:91], v[210:213], v[164:167], v[88:91]
	v_mfma_f32_16x16x32_bf16 v[84:87], v[202:205], v[172:175], v[84:87]
	v_mfma_f32_16x16x32_bf16 v[80:83], v[210:213], v[172:175], v[80:83]
	v_mfma_f32_16x16x32_bf16 v[76:79], v[202:205], v[180:183], v[76:79]
	v_mfma_f32_16x16x32_bf16 v[72:75], v[210:213], v[180:183], v[72:75]
	v_mfma_f32_16x16x32_bf16 v[68:71], v[202:205], v[194:197], v[68:71]
	v_mfma_f32_16x16x32_bf16 v[64:67], v[210:213], v[194:197], v[64:67]
	s_mov_b32 m0, s38
	v_lshl_add_u64 v[216:217], s[36:37], 0, v[134:135]
	s_barrier
	ds_read_b128 v[160:163], v142 offset:16384
	ds_read_b128 v[164:167], v142 offset:17408
	ds_read_b128 v[168:171], v142 offset:18432
	ds_read_b128 v[172:175], v142 offset:19456
	ds_read_b128 v[176:179], v142 offset:20480
	ds_read_b128 v[180:183], v142 offset:21504
	ds_read_b128 v[186:189], v142 offset:22528
	ds_read_b128 v[194:197], v142 offset:23552
	global_load_lds_dwordx4 v[216:217], off
	v_lshl_add_u64 v[242:243], s[36:37], 0, v[130:131]
	s_mov_b32 m0, s41
	s_nop 0
	global_load_lds_dwordx4 v[242:243], off
	s_barrier
	s_waitcnt lgkmcnt(0)
	s_waitcnt lgkmcnt(0)
	v_mfma_f32_16x16x32_bf16 v[60:63], v[144:147], v[160:163], v[60:63]
	v_mfma_f32_16x16x32_bf16 v[56:59], v[152:155], v[160:163], v[56:59]
	v_mfma_f32_16x16x32_bf16 v[52:55], v[144:147], v[168:171], v[52:55]
	v_mfma_f32_16x16x32_bf16 v[48:51], v[152:155], v[168:171], v[48:51]
	v_mfma_f32_16x16x32_bf16 v[44:47], v[144:147], v[176:179], v[44:47]
	v_mfma_f32_16x16x32_bf16 v[40:43], v[152:155], v[176:179], v[40:43]
	v_mfma_f32_16x16x32_bf16 v[36:39], v[144:147], v[186:189], v[36:39]
	v_mfma_f32_16x16x32_bf16 v[32:35], v[152:155], v[186:189], v[32:35]
	v_mfma_f32_16x16x32_bf16 v[60:63], v[148:151], v[164:167], v[60:63]
	v_mfma_f32_16x16x32_bf16 v[56:59], v[156:159], v[164:167], v[56:59]
	v_mfma_f32_16x16x32_bf16 v[52:55], v[148:151], v[172:175], v[52:55]
	v_mfma_f32_16x16x32_bf16 v[48:51], v[156:159], v[172:175], v[48:51]
	v_mfma_f32_16x16x32_bf16 v[44:47], v[148:151], v[180:183], v[44:47]
	v_mfma_f32_16x16x32_bf16 v[40:43], v[156:159], v[180:183], v[40:43]
	v_mfma_f32_16x16x32_bf16 v[36:39], v[148:151], v[194:197], v[36:39]
	v_mfma_f32_16x16x32_bf16 v[32:35], v[156:159], v[194:197], v[32:35]
	s_barrier
	s_add_u32 s66, s34, 0x800000
	s_addc_u32 s67, s35, 0
	s_mov_b32 m0, s42
	v_lshl_add_u64 v[144:145], s[66:67], 0, v[132:133]
	global_load_lds_dwordx4 v[144:145], off
	v_lshl_add_u64 v[144:145], s[66:67], 0, v[128:129]
	s_mov_b32 m0, s43
	s_nop 0
	global_load_lds_dwordx4 v[144:145], off
	s_waitcnt vmcnt(6)
	s_barrier
	v_mfma_f32_16x16x32_bf16 v[28:31], v[198:201], v[160:163], v[28:31]
	v_mfma_f32_16x16x32_bf16 v[24:27], v[206:209], v[160:163], v[24:27]
	v_mfma_f32_16x16x32_bf16 v[20:23], v[198:201], v[168:171], v[20:23]
	v_mfma_f32_16x16x32_bf16 v[16:19], v[206:209], v[168:171], v[16:19]
	v_mfma_f32_16x16x32_bf16 v[12:15], v[198:201], v[176:179], v[12:15]
	v_mfma_f32_16x16x32_bf16 v[8:11], v[206:209], v[176:179], v[8:11]
	v_mfma_f32_16x16x32_bf16 v[4:7], v[198:201], v[186:189], v[4:7]
	v_mfma_f32_16x16x32_bf16 v[0:3], v[206:209], v[186:189], v[0:3]
	v_mfma_f32_16x16x32_bf16 v[28:31], v[202:205], v[164:167], v[28:31]
	v_mfma_f32_16x16x32_bf16 v[24:27], v[210:213], v[164:167], v[24:27]
	v_mfma_f32_16x16x32_bf16 v[20:23], v[202:205], v[172:175], v[20:23]
	v_mfma_f32_16x16x32_bf16 v[16:19], v[210:213], v[172:175], v[16:19]
	v_mfma_f32_16x16x32_bf16 v[12:15], v[202:205], v[180:183], v[12:15]
	v_mfma_f32_16x16x32_bf16 v[8:11], v[210:213], v[180:183], v[8:11]
	v_mfma_f32_16x16x32_bf16 v[4:7], v[202:205], v[194:197], v[4:7]
	v_mfma_f32_16x16x32_bf16 v[0:3], v[210:213], v[194:197], v[0:3]
	v_or_b32_e32 v141, 0x18000, v143
	v_add_u32_e32 v148, 0x18400, v143
	s_barrier
	ds_read_b128 v[144:147], v141
	ds_read_b128 v[148:151], v148
	v_add_u32_e32 v141, 0x18800, v143
	v_add_u32_e32 v156, 0x18c00, v143
	ds_read_b128 v[152:155], v141
	ds_read_b128 v[156:159], v156
	s_add_u32 s36, s36, 0x100000
	s_addc_u32 s37, s37, 0
	s_mov_b32 m0, s44
	v_lshl_add_u64 v[198:199], s[36:37], 0, v[134:135]
	ds_read_b128 v[160:163], v142 offset:32768
	ds_read_b128 v[164:167], v142 offset:33792
	ds_read_b128 v[168:171], v142 offset:34816
	ds_read_b128 v[172:175], v142 offset:35840
	ds_read_b128 v[176:179], v142 offset:36864
	ds_read_b128 v[180:183], v142 offset:37888
	ds_read_b128 v[186:189], v142 offset:38912
	ds_read_b128 v[194:197], v142 offset:39936
	global_load_lds_dwordx4 v[198:199], off
	v_lshl_add_u64 v[198:199], s[36:37], 0, v[130:131]
	s_mov_b32 m0, s45
	s_nop 0
	global_load_lds_dwordx4 v[198:199], off
	s_waitcnt lgkmcnt(8)
	s_barrier
	s_waitcnt lgkmcnt(0)
	s_waitcnt lgkmcnt(0)
	v_mfma_f32_16x16x32_bf16 v[124:127], v[144:147], v[160:163], v[124:127]
	v_mfma_f32_16x16x32_bf16 v[120:123], v[152:155], v[160:163], v[120:123]
	v_mfma_f32_16x16x32_bf16 v[116:119], v[144:147], v[168:171], v[116:119]
	v_mfma_f32_16x16x32_bf16 v[112:115], v[152:155], v[168:171], v[112:115]
	v_mfma_f32_16x16x32_bf16 v[108:111], v[144:147], v[176:179], v[108:111]
	v_mfma_f32_16x16x32_bf16 v[104:107], v[152:155], v[176:179], v[104:107]
	v_mfma_f32_16x16x32_bf16 v[100:103], v[144:147], v[186:189], v[100:103]
	v_mfma_f32_16x16x32_bf16 v[96:99], v[152:155], v[186:189], v[96:99]
	v_mfma_f32_16x16x32_bf16 v[124:127], v[148:151], v[164:167], v[124:127]
	v_mfma_f32_16x16x32_bf16 v[120:123], v[156:159], v[164:167], v[120:123]
	v_mfma_f32_16x16x32_bf16 v[116:119], v[148:151], v[172:175], v[116:119]
	v_mfma_f32_16x16x32_bf16 v[112:115], v[156:159], v[172:175], v[112:115]
	v_mfma_f32_16x16x32_bf16 v[108:111], v[148:151], v[180:183], v[108:111]
	v_mfma_f32_16x16x32_bf16 v[104:107], v[156:159], v[180:183], v[104:107]
	v_mfma_f32_16x16x32_bf16 v[100:103], v[148:151], v[194:197], v[100:103]
	v_mfma_f32_16x16x32_bf16 v[96:99], v[156:159], v[194:197], v[96:99]
	s_barrier
	v_or_b32_e32 v141, 0x1c000, v143
	s_mov_b32 m0, s46
	v_add_u32_e32 v192, 0x1c400, v143
	ds_read_b128 v[198:201], v141
	ds_read_b128 v[202:205], v192
	v_add_u32_e32 v141, 0x1c800, v143
	v_lshl_add_u64 v[190:191], v[190:191], 0, s[24:25]
	v_add_u32_e32 v192, 0x1cc00, v143
	ds_read_b128 v[206:209], v141
	ds_read_b128 v[210:213], v192
	global_load_lds_dwordx4 v[190:191], off
	v_lshl_add_u64 v[190:191], v[214:215], 0, s[24:25]
	s_mov_b32 m0, s47
	s_nop 0
	global_load_lds_dwordx4 v[190:191], off
	s_barrier
	s_waitcnt lgkmcnt(0)
	s_waitcnt lgkmcnt(0)
	v_mfma_f32_16x16x32_bf16 v[92:95], v[198:201], v[160:163], v[92:95]
	v_mfma_f32_16x16x32_bf16 v[88:91], v[206:209], v[160:163], v[88:91]
	v_mfma_f32_16x16x32_bf16 v[84:87], v[198:201], v[168:171], v[84:87]
	v_mfma_f32_16x16x32_bf16 v[80:83], v[206:209], v[168:171], v[80:83]
	v_mfma_f32_16x16x32_bf16 v[76:79], v[198:201], v[176:179], v[76:79]
	v_mfma_f32_16x16x32_bf16 v[72:75], v[206:209], v[176:179], v[72:75]
	v_mfma_f32_16x16x32_bf16 v[68:71], v[198:201], v[186:189], v[68:71]
	v_mfma_f32_16x16x32_bf16 v[64:67], v[206:209], v[186:189], v[64:67]
	v_mfma_f32_16x16x32_bf16 v[92:95], v[202:205], v[164:167], v[92:95]
	v_mfma_f32_16x16x32_bf16 v[88:91], v[210:213], v[164:167], v[88:91]
	v_mfma_f32_16x16x32_bf16 v[84:87], v[202:205], v[172:175], v[84:87]
	v_mfma_f32_16x16x32_bf16 v[80:83], v[210:213], v[172:175], v[80:83]
	v_mfma_f32_16x16x32_bf16 v[76:79], v[202:205], v[180:183], v[76:79]
	v_mfma_f32_16x16x32_bf16 v[72:75], v[210:213], v[180:183], v[72:75]
	v_mfma_f32_16x16x32_bf16 v[68:71], v[202:205], v[194:197], v[68:71]
	v_mfma_f32_16x16x32_bf16 v[64:67], v[210:213], v[194:197], v[64:67]
	s_mov_b32 m0, s48
	v_lshl_add_u64 v[190:191], v[216:217], 0, s[24:25]
	s_barrier
	ds_read_b128 v[160:163], v142 offset:49152
	ds_read_b128 v[164:167], v142 offset:50176
	ds_read_b128 v[168:171], v142 offset:51200
	ds_read_b128 v[172:175], v142 offset:52224
	ds_read_b128 v[176:179], v142 offset:53248
	ds_read_b128 v[180:183], v142 offset:54272
	ds_read_b128 v[186:189], v142 offset:55296
	ds_read_b128 v[194:197], v142 offset:56320
	global_load_lds_dwordx4 v[190:191], off
	v_lshl_add_u64 v[190:191], v[242:243], 0, s[24:25]
	s_mov_b32 m0, s49
	s_nop 0
	global_load_lds_dwordx4 v[190:191], off
	s_barrier
	s_waitcnt lgkmcnt(0)
	s_waitcnt lgkmcnt(0)
	v_mfma_f32_16x16x32_bf16 v[60:63], v[144:147], v[160:163], v[60:63]
	v_mfma_f32_16x16x32_bf16 v[56:59], v[152:155], v[160:163], v[56:59]
	v_mfma_f32_16x16x32_bf16 v[52:55], v[144:147], v[168:171], v[52:55]
	v_mfma_f32_16x16x32_bf16 v[48:51], v[152:155], v[168:171], v[48:51]
	v_mfma_f32_16x16x32_bf16 v[44:47], v[144:147], v[176:179], v[44:47]
	v_mfma_f32_16x16x32_bf16 v[40:43], v[152:155], v[176:179], v[40:43]
	v_mfma_f32_16x16x32_bf16 v[36:39], v[144:147], v[186:189], v[36:39]
	v_mfma_f32_16x16x32_bf16 v[32:35], v[152:155], v[186:189], v[32:35]
	v_mfma_f32_16x16x32_bf16 v[60:63], v[148:151], v[164:167], v[60:63]
	v_mfma_f32_16x16x32_bf16 v[56:59], v[156:159], v[164:167], v[56:59]
	v_mfma_f32_16x16x32_bf16 v[52:55], v[148:151], v[172:175], v[52:55]
	v_mfma_f32_16x16x32_bf16 v[48:51], v[156:159], v[172:175], v[48:51]
	v_mfma_f32_16x16x32_bf16 v[44:47], v[148:151], v[180:183], v[44:47]
	v_mfma_f32_16x16x32_bf16 v[40:43], v[156:159], v[180:183], v[40:43]
	v_mfma_f32_16x16x32_bf16 v[36:39], v[148:151], v[194:197], v[36:39]
	v_mfma_f32_16x16x32_bf16 v[32:35], v[156:159], v[194:197], v[32:35]
	s_barrier
	s_add_u32 s34, s34, 0x800080
	s_addc_u32 s35, s35, 0
	s_mov_b32 m0, s50
	v_lshl_add_u64 v[144:145], s[34:35], 0, v[132:133]
	global_load_lds_dwordx4 v[144:145], off
	v_lshl_add_u64 v[144:145], s[34:35], 0, v[128:129]
	s_mov_b32 m0, s51
	s_nop 0
	global_load_lds_dwordx4 v[144:145], off
	s_waitcnt vmcnt(6)
	s_barrier
	v_mfma_f32_16x16x32_bf16 v[28:31], v[198:201], v[160:163], v[28:31]
	v_mfma_f32_16x16x32_bf16 v[24:27], v[206:209], v[160:163], v[24:27]
	v_mfma_f32_16x16x32_bf16 v[20:23], v[198:201], v[168:171], v[20:23]
	v_mfma_f32_16x16x32_bf16 v[16:19], v[206:209], v[168:171], v[16:19]
	v_mfma_f32_16x16x32_bf16 v[12:15], v[198:201], v[176:179], v[12:15]
	v_mfma_f32_16x16x32_bf16 v[8:11], v[206:209], v[176:179], v[8:11]
	v_mfma_f32_16x16x32_bf16 v[4:7], v[198:201], v[186:189], v[4:7]
	v_mfma_f32_16x16x32_bf16 v[0:3], v[206:209], v[186:189], v[0:3]
	v_mfma_f32_16x16x32_bf16 v[28:31], v[202:205], v[164:167], v[28:31]
	v_mfma_f32_16x16x32_bf16 v[24:27], v[210:213], v[164:167], v[24:27]
	v_mfma_f32_16x16x32_bf16 v[20:23], v[202:205], v[172:175], v[20:23]
	v_mfma_f32_16x16x32_bf16 v[16:19], v[210:213], v[172:175], v[16:19]
	v_mfma_f32_16x16x32_bf16 v[12:15], v[202:205], v[180:183], v[12:15]
	v_mfma_f32_16x16x32_bf16 v[8:11], v[210:213], v[180:183], v[8:11]
	v_mfma_f32_16x16x32_bf16 v[4:7], v[202:205], v[194:197], v[4:7]
	v_mfma_f32_16x16x32_bf16 v[0:3], v[210:213], v[194:197], v[0:3]
	s_add_i32 s96, s96, 2
	s_add_u32 s30, s30, 0x100
	s_addc_u32 s31, s31, 0
	s_add_u32 s26, s26, 0x100
	s_addc_u32 s27, s27, 0
	s_cmp_gt_u32 s96, 13
	s_barrier
	s_cbranch_scc0 .LBB0_234
	s_lshl_b32 s20, s71, 7
	s_lshl_b32 s26, s56, 4
	s_or_b32 s27, s26, s20
	s_add_i32 s34, s27, s52
	s_lshl_b32 s88, s70, 19
	v_readlane_b32 s72, v253, 16
	s_ashr_i32 s35, s34, 31
	s_lshl_b64 s[30:31], s[88:89], 4
	v_readlane_b32 s74, v253, 18
	v_readlane_b32 s75, v253, 19
	s_add_u32 s27, s74, s30
	s_addc_u32 s30, s75, s31
	s_lshl_b64 s[34:35], s[34:35], 13
	s_add_u32 s31, s27, s34
	s_addc_u32 s33, s30, s35
	s_add_u32 s34, s31, s63
	s_addc_u32 s35, s33, 0
	v_cvt_pk_bf16_f32 v124, v124, v125
	v_cvt_pk_bf16_f32 v125, v126, v127
	v_cvt_pk_bf16_f32 v126, v120, v121
	v_lshl_add_u64 v[120:121], s[34:35], 0, v[184:185]
	s_add_i32 s34, s54, s20
	s_add_i32 s34, s34, s26
	s_ashr_i32 s35, s34, 31
	s_lshl_b64 s[34:35], s[34:35], 13
	s_add_u32 s36, s27, s34
	s_addc_u32 s37, s30, s35
	s_add_u32 s34, s36, s63
	s_addc_u32 s35, s37, 0
	v_cvt_pk_bf16_f32 v116, v116, v117
	v_cvt_pk_bf16_f32 v117, v118, v119
	v_cvt_pk_bf16_f32 v118, v112, v113
	v_lshl_add_u64 v[112:113], s[34:35], 0, v[184:185]
	s_add_i32 s34, s55, s20
	s_add_i32 s34, s34, s26
	s_ashr_i32 s35, s34, 31
	s_lshl_b64 s[34:35], s[34:35], 13
	s_add_u32 s66, s27, s34
	s_addc_u32 s67, s30, s35
	s_add_u32 s34, s66, s63
	s_addc_u32 s35, s67, 0
	v_cvt_pk_bf16_f32 v108, v108, v109
	v_cvt_pk_bf16_f32 v109, v110, v111
	v_cvt_pk_bf16_f32 v110, v104, v105
	v_lshl_add_u64 v[104:105], s[34:35], 0, v[184:185]
	s_add_i32 s34, s58, s20
	s_add_i32 s34, s34, s26
	s_ashr_i32 s35, s34, 31
	s_lshl_b64 s[34:35], s[34:35], 13
	s_add_u32 s70, s27, s34
	s_addc_u32 s71, s30, s35
	s_add_u32 s34, s70, s63
	s_addc_u32 s35, s71, 0
	v_cvt_pk_bf16_f32 v100, v100, v101
	v_cvt_pk_bf16_f32 v101, v102, v103
	v_cvt_pk_bf16_f32 v102, v96, v97
	v_lshl_add_u64 v[96:97], s[34:35], 0, v[184:185]
	s_add_u32 s34, s31, s64
	s_addc_u32 s35, s33, 0
	v_cvt_pk_bf16_f32 v92, v92, v93
	v_cvt_pk_bf16_f32 v93, v94, v95
	v_cvt_pk_bf16_f32 v94, v88, v89
	v_lshl_add_u64 v[88:89], s[34:35], 0, v[184:185]
	s_add_u32 s34, s36, s64
	s_addc_u32 s35, s37, 0
	v_cvt_pk_bf16_f32 v84, v84, v85
	v_cvt_pk_bf16_f32 v85, v86, v87
	v_cvt_pk_bf16_f32 v86, v80, v81
	v_lshl_add_u64 v[80:81], s[34:35], 0, v[184:185]
	s_add_u32 s34, s66, s64
	s_addc_u32 s35, s67, 0
	v_cvt_pk_bf16_f32 v76, v76, v77
	v_cvt_pk_bf16_f32 v77, v78, v79
	v_cvt_pk_bf16_f32 v78, v72, v73
	v_lshl_add_u64 v[72:73], s[34:35], 0, v[184:185]
	s_add_u32 s34, s70, s64
	s_addc_u32 s35, s71, 0
	s_add_i32 s31, s53, s20
	v_cvt_pk_bf16_f32 v68, v68, v69
	v_cvt_pk_bf16_f32 v69, v70, v71
	v_cvt_pk_bf16_f32 v70, v64, v65
	v_lshl_add_u64 v[64:65], s[34:35], 0, v[184:185]
	s_add_i32 s34, s31, s26
	s_ashr_i32 s35, s34, 31
	s_lshl_b64 s[34:35], s[34:35], 13
	s_add_u32 s31, s27, s34
	s_addc_u32 s33, s30, s35
	s_add_u32 s34, s31, s63
	s_addc_u32 s35, s33, 0
	v_cvt_pk_bf16_f32 v60, v60, v61
	v_cvt_pk_bf16_f32 v61, v62, v63
	v_cvt_pk_bf16_f32 v62, v56, v57
	v_lshl_add_u64 v[56:57], s[34:35], 0, v[184:185]
	s_add_i32 s34, s59, s20
	s_add_i32 s34, s34, s26
	s_ashr_i32 s35, s34, 31
	s_lshl_b64 s[34:35], s[34:35], 13
	s_add_u32 s36, s27, s34
	s_addc_u32 s37, s30, s35
	s_add_u32 s34, s36, s63
	s_addc_u32 s35, s37, 0
	v_cvt_pk_bf16_f32 v52, v52, v53
	v_cvt_pk_bf16_f32 v53, v54, v55
	v_cvt_pk_bf16_f32 v54, v48, v49
	v_lshl_add_u64 v[48:49], s[34:35], 0, v[184:185]
	s_add_i32 s34, s60, s20
	s_add_i32 s34, s34, s26
	s_ashr_i32 s35, s34, 31
	s_lshl_b64 s[34:35], s[34:35], 13
	s_add_u32 s66, s27, s34
	s_addc_u32 s67, s30, s35
	s_add_u32 s34, s66, s63
	s_addc_u32 s35, s67, 0
	s_add_i32 s20, s61, s20
	v_cvt_pk_bf16_f32 v44, v44, v45
	v_cvt_pk_bf16_f32 v45, v46, v47
	v_cvt_pk_bf16_f32 v46, v40, v41
	v_lshl_add_u64 v[40:41], s[34:35], 0, v[184:185]
	s_add_i32 s34, s20, s26
	s_ashr_i32 s35, s34, 31
	s_lshl_b64 s[34:35], s[34:35], 13
	s_add_u32 s20, s27, s34
	s_addc_u32 s30, s30, s35
	s_add_u32 s26, s20, s63
	s_addc_u32 s27, s30, 0
	v_cvt_pk_bf16_f32 v36, v36, v37
	v_cvt_pk_bf16_f32 v37, v38, v39
	v_cvt_pk_bf16_f32 v38, v32, v33
	v_lshl_add_u64 v[32:33], s[26:27], 0, v[184:185]
	s_add_u32 s26, s31, s64
	s_addc_u32 s27, s33, 0
	v_cvt_pk_bf16_f32 v28, v28, v29
	v_cvt_pk_bf16_f32 v29, v30, v31
	v_cvt_pk_bf16_f32 v30, v24, v25
	v_lshl_add_u64 v[24:25], s[26:27], 0, v[184:185]
	s_add_u32 s26, s36, s64
	s_addc_u32 s27, s37, 0
	v_cvt_pk_bf16_f32 v20, v20, v21
	v_cvt_pk_bf16_f32 v21, v22, v23
	v_cvt_pk_bf16_f32 v22, v16, v17
	v_lshl_add_u64 v[16:17], s[26:27], 0, v[184:185]
	s_add_u32 s26, s66, s64
	s_addc_u32 s27, s67, 0
	v_cvt_pk_bf16_f32 v12, v12, v13
	v_cvt_pk_bf16_f32 v13, v14, v15
	v_cvt_pk_bf16_f32 v14, v8, v9
	v_lshl_add_u64 v[8:9], s[26:27], 0, v[184:185]
	s_add_u32 s26, s20, s64
	s_addc_u32 s27, s30, 0
	v_mov_b32_e32 v141, v185
	v_cvt_pk_bf16_f32 v4, v4, v5
	v_cvt_pk_bf16_f32 v5, v6, v7
	v_cvt_pk_bf16_f32 v6, v0, v1
	v_lshl_add_u64 v[0:1], s[26:27], 0, v[184:185]
	v_readlane_b32 s78, v253, 22
	v_readlane_b32 s79, v253, 23
	v_lshl_add_u64 v[120:121], v[120:121], 0, v[140:141]
	v_lshl_add_u64 v[112:113], v[112:113], 0, v[140:141]
	v_lshl_add_u64 v[104:105], v[104:105], 0, v[140:141]
	v_lshl_add_u64 v[96:97], v[96:97], 0, v[140:141]
	v_lshl_add_u64 v[88:89], v[88:89], 0, v[140:141]
	v_lshl_add_u64 v[80:81], v[80:81], 0, v[140:141]
	v_lshl_add_u64 v[72:73], v[72:73], 0, v[140:141]
	v_lshl_add_u64 v[64:65], v[64:65], 0, v[140:141]
	v_lshl_add_u64 v[56:57], v[56:57], 0, v[140:141]
	v_lshl_add_u64 v[48:49], v[48:49], 0, v[140:141]
	v_lshl_add_u64 v[40:41], v[40:41], 0, v[140:141]
	v_lshl_add_u64 v[32:33], v[32:33], 0, v[140:141]
	v_lshl_add_u64 v[24:25], v[24:25], 0, v[140:141]
	v_lshl_add_u64 v[16:17], v[16:17], 0, v[140:141]
	v_lshl_add_u64 v[8:9], v[8:9], 0, v[140:141]
	v_lshl_add_u64 v[0:1], v[0:1], 0, v[140:141]
	s_and_b64 vcc, exec, s[0:1]
	s_mov_b32 s71, s65
	s_mov_b32 s70, s68
	s_mov_b32 s56, s69
	v_readlane_b32 s96, v255, 22
	v_cvt_pk_bf16_f32 v127, v122, v123
	v_readlane_b32 s73, v253, 17
	v_readlane_b32 s76, v253, 20
	v_readlane_b32 s77, v253, 21
	v_readlane_b32 s80, v253, 24
	v_readlane_b32 s81, v253, 25
	v_readlane_b32 s82, v253, 26
	v_readlane_b32 s83, v253, 27
	v_readlane_b32 s84, v253, 28
	v_readlane_b32 s85, v253, 29
	v_readlane_b32 s86, v253, 30
	v_readlane_b32 s87, v253, 31
	global_store_dwordx4 v[120:121], v[124:127], off
	v_cvt_pk_bf16_f32 v119, v114, v115
	global_store_dwordx4 v[112:113], v[116:119], off
	v_cvt_pk_bf16_f32 v111, v106, v107
	global_store_dwordx4 v[104:105], v[108:111], off
	v_cvt_pk_bf16_f32 v103, v98, v99
	global_store_dwordx4 v[96:97], v[100:103], off
	v_cvt_pk_bf16_f32 v95, v90, v91
	global_store_dwordx4 v[88:89], v[92:95], off
	v_cvt_pk_bf16_f32 v87, v82, v83
	global_store_dwordx4 v[80:81], v[84:87], off
	v_cvt_pk_bf16_f32 v79, v74, v75
	global_store_dwordx4 v[72:73], v[76:79], off
	v_cvt_pk_bf16_f32 v71, v66, v67
	global_store_dwordx4 v[64:65], v[68:71], off
	v_cvt_pk_bf16_f32 v63, v58, v59
	global_store_dwordx4 v[56:57], v[60:63], off
	v_cvt_pk_bf16_f32 v55, v50, v51
	global_store_dwordx4 v[48:49], v[52:55], off
	v_cvt_pk_bf16_f32 v47, v42, v43
	global_store_dwordx4 v[40:41], v[44:47], off
	v_cvt_pk_bf16_f32 v39, v34, v35
	global_store_dwordx4 v[32:33], v[36:39], off
	v_cvt_pk_bf16_f32 v31, v26, v27
	global_store_dwordx4 v[24:25], v[28:31], off
	v_cvt_pk_bf16_f32 v23, v18, v19
	global_store_dwordx4 v[16:17], v[20:23], off
	v_cvt_pk_bf16_f32 v15, v10, v11
	global_store_dwordx4 v[8:9], v[12:15], off
	v_cvt_pk_bf16_f32 v7, v2, v3
	global_store_dwordx4 v[0:1], v[4:7], off
	s_cbranch_vccz .LBB0_233
	v_readlane_b32 s84, v255, 43
	s_waitcnt vmcnt(0)
	v_readlane_b32 s86, v255, 45
	v_readlane_b32 s87, v255, 46
	v_readlane_b32 s72, v255, 23
	v_readlane_b32 s86, v255, 31
	s_cmpk_gt_u32 s93, 0xff
	v_readlane_b32 s85, v255, 44
	v_readlane_b32 s73, v255, 24
	v_readlane_b32 s74, v255, 25
	v_readlane_b32 s75, v255, 26
	v_readlane_b32 s76, v255, 27
	v_readlane_b32 s77, v255, 28
	v_readlane_b32 s78, v255, 29
	v_readlane_b32 s79, v255, 30
	s_mov_b32 s80, s57
	v_readlane_b32 s93, v255, 34
	v_readlane_b32 s81, v255, 33
	v_readlane_b32 s87, v255, 32
	s_mov_b32 s70, 0xbfb8aa3b
	s_mov_b32 s71, 0x42ce8ed0
	s_cbranch_scc1 .LBB0_238
	s_barrier

.LBB0_245:
	v_or_b32_e32 v144, 0x10000, v143
	v_add_u32_e32 v148, 0x10400, v143
	v_add_u32_e32 v152, 0x10800, v143
	v_add_u32_e32 v156, 0x10c00, v143
	ds_read_b128 v[144:147], v144
	ds_read_b128 v[148:151], v148
	ds_read_b128 v[152:155], v152
	ds_read_b128 v[156:159], v156
	s_add_u32 s34, s30, 0xfffe0080
	s_addc_u32 s35, s31, -1
	s_cmp_eq_u32 s61, 4
	s_cselect_b32 s37, s79, s35
	s_cselect_b32 s36, s78, s34
	s_cselect_b32 s35, s20, s27
	s_cselect_b32 s34, s60, s26
	v_lshl_add_u64 v[190:191], s[30:31], 0, v[138:139]
	s_add_i32 m0, s38, 0xc000
	ds_read_b128 v[160:163], v142
	ds_read_b128 v[164:167], v142 offset:1024
	ds_read_b128 v[168:171], v142 offset:2048
	ds_read_b128 v[172:175], v142 offset:3072
	ds_read_b128 v[176:179], v142 offset:4096
	ds_read_b128 v[180:183], v142 offset:5120
	ds_read_b128 v[186:189], v142 offset:6144
	ds_read_b128 v[194:197], v142 offset:7168
	global_load_lds_dwordx4 v[190:191], off
	v_lshl_add_u64 v[190:191], s[30:31], 0, v[140:141]
	s_add_i32 m0, s38, 0xe000
	s_nop 0
	global_load_lds_dwordx4 v[190:191], off
	s_waitcnt lgkmcnt(8)
	s_barrier
	s_waitcnt lgkmcnt(0)
	s_waitcnt lgkmcnt(0)
	v_mfma_f32_16x16x32_bf16 v[124:127], v[144:147], v[160:163], v[124:127]
	v_mfma_f32_16x16x32_bf16 v[120:123], v[152:155], v[160:163], v[120:123]
	v_mfma_f32_16x16x32_bf16 v[116:119], v[144:147], v[168:171], v[116:119]
	v_mfma_f32_16x16x32_bf16 v[112:115], v[152:155], v[168:171], v[112:115]
	v_mfma_f32_16x16x32_bf16 v[108:111], v[144:147], v[176:179], v[108:111]
	v_mfma_f32_16x16x32_bf16 v[104:107], v[152:155], v[176:179], v[104:107]
	v_mfma_f32_16x16x32_bf16 v[100:103], v[144:147], v[186:189], v[100:103]
	v_mfma_f32_16x16x32_bf16 v[96:99], v[152:155], v[186:189], v[96:99]
	v_mfma_f32_16x16x32_bf16 v[124:127], v[148:151], v[164:167], v[124:127]
	v_mfma_f32_16x16x32_bf16 v[120:123], v[156:159], v[164:167], v[120:123]
	v_mfma_f32_16x16x32_bf16 v[116:119], v[148:151], v[172:175], v[116:119]
	v_mfma_f32_16x16x32_bf16 v[112:115], v[156:159], v[172:175], v[112:115]
	v_mfma_f32_16x16x32_bf16 v[108:111], v[148:151], v[180:183], v[108:111]
	v_mfma_f32_16x16x32_bf16 v[104:107], v[156:159], v[180:183], v[104:107]
	v_mfma_f32_16x16x32_bf16 v[100:103], v[148:151], v[194:197], v[100:103]
	v_mfma_f32_16x16x32_bf16 v[96:99], v[156:159], v[194:197], v[96:99]
	s_barrier
	v_or_b32_e32 v190, 0x14000, v143
	v_add_u32_e32 v191, 0x14400, v143
	ds_read_b128 v[198:201], v190
	ds_read_b128 v[202:205], v191
	v_add_u32_e32 v190, 0x14800, v143
	v_add_u32_e32 v191, 0x14c00, v143
	s_mov_b32 m0, s1
	ds_read_b128 v[206:209], v190
	ds_read_b128 v[210:213], v191
	v_lshl_add_u64 v[190:191], s[34:35], 0, v[184:185]
	global_load_lds_dwordx4 v[190:191], off
	v_lshl_add_u64 v[214:215], s[34:35], 0, v[128:129]
	s_mov_b32 m0, s39
	s_nop 0
	global_load_lds_dwordx4 v[214:215], off
	s_barrier
	s_waitcnt lgkmcnt(0)
	s_waitcnt lgkmcnt(0)
	v_mfma_f32_16x16x32_bf16 v[92:95], v[198:201], v[160:163], v[92:95]
	v_mfma_f32_16x16x32_bf16 v[88:91], v[206:209], v[160:163], v[88:91]
	v_mfma_f32_16x16x32_bf16 v[84:87], v[198:201], v[168:171], v[84:87]
	v_mfma_f32_16x16x32_bf16 v[80:83], v[206:209], v[168:171], v[80:83]
	v_mfma_f32_16x16x32_bf16 v[76:79], v[198:201], v[176:179], v[76:79]
	v_mfma_f32_16x16x32_bf16 v[72:75], v[206:209], v[176:179], v[72:75]
	v_mfma_f32_16x16x32_bf16 v[68:71], v[198:201], v[186:189], v[68:71]
	v_mfma_f32_16x16x32_bf16 v[64:67], v[206:209], v[186:189], v[64:67]
	v_mfma_f32_16x16x32_bf16 v[92:95], v[202:205], v[164:167], v[92:95]
	v_mfma_f32_16x16x32_bf16 v[88:91], v[210:213], v[164:167], v[88:91]
	v_mfma_f32_16x16x32_bf16 v[84:87], v[202:205], v[172:175], v[84:87]
	v_mfma_f32_16x16x32_bf16 v[80:83], v[210:213], v[172:175], v[80:83]
	v_mfma_f32_16x16x32_bf16 v[76:79], v[202:205], v[180:183], v[76:79]
	v_mfma_f32_16x16x32_bf16 v[72:75], v[210:213], v[180:183], v[72:75]
	v_mfma_f32_16x16x32_bf16 v[68:71], v[202:205], v[194:197], v[68:71]
	v_mfma_f32_16x16x32_bf16 v[64:67], v[210:213], v[194:197], v[64:67]
	s_mov_b32 m0, s38
	v_lshl_add_u64 v[216:217], s[36:37], 0, v[132:133]
	s_barrier
	ds_read_b128 v[160:163], v142 offset:16384
	ds_read_b128 v[164:167], v142 offset:17408
	ds_read_b128 v[168:171], v142 offset:18432
	ds_read_b128 v[172:175], v142 offset:19456
	ds_read_b128 v[176:179], v142 offset:20480
	ds_read_b128 v[180:183], v142 offset:21504
	ds_read_b128 v[186:189], v142 offset:22528
	ds_read_b128 v[194:197], v142 offset:23552
	global_load_lds_dwordx4 v[216:217], off
	v_lshl_add_u64 v[242:243], s[36:37], 0, v[130:131]
	s_mov_b32 m0, s40
	s_nop 0
	global_load_lds_dwordx4 v[242:243], off
	s_barrier
	s_waitcnt lgkmcnt(0)
	s_waitcnt lgkmcnt(0)
	v_mfma_f32_16x16x32_bf16 v[60:63], v[144:147], v[160:163], v[60:63]
	v_mfma_f32_16x16x32_bf16 v[56:59], v[152:155], v[160:163], v[56:59]
	v_mfma_f32_16x16x32_bf16 v[52:55], v[144:147], v[168:171], v[52:55]
	v_mfma_f32_16x16x32_bf16 v[48:51], v[152:155], v[168:171], v[48:51]
	v_mfma_f32_16x16x32_bf16 v[44:47], v[144:147], v[176:179], v[44:47]
	v_mfma_f32_16x16x32_bf16 v[40:43], v[152:155], v[176:179], v[40:43]
	v_mfma_f32_16x16x32_bf16 v[36:39], v[144:147], v[186:189], v[36:39]
	v_mfma_f32_16x16x32_bf16 v[32:35], v[152:155], v[186:189], v[32:35]
	v_mfma_f32_16x16x32_bf16 v[60:63], v[148:151], v[164:167], v[60:63]
	v_mfma_f32_16x16x32_bf16 v[56:59], v[156:159], v[164:167], v[56:59]
	v_mfma_f32_16x16x32_bf16 v[52:55], v[148:151], v[172:175], v[52:55]
	v_mfma_f32_16x16x32_bf16 v[48:51], v[156:159], v[172:175], v[48:51]
	v_mfma_f32_16x16x32_bf16 v[44:47], v[148:151], v[180:183], v[44:47]
	v_mfma_f32_16x16x32_bf16 v[40:43], v[156:159], v[180:183], v[40:43]
	v_mfma_f32_16x16x32_bf16 v[36:39], v[148:151], v[194:197], v[36:39]
	v_mfma_f32_16x16x32_bf16 v[32:35], v[156:159], v[194:197], v[32:35]
	s_barrier
	s_add_u32 s62, s34, 0x100000
	s_addc_u32 s63, s35, 0
	s_mov_b32 m0, s41
	v_lshl_add_u64 v[144:145], s[62:63], 0, v[184:185]
	global_load_lds_dwordx4 v[144:145], off
	v_lshl_add_u64 v[144:145], s[62:63], 0, v[128:129]
	s_mov_b32 m0, s42
	s_nop 0
	global_load_lds_dwordx4 v[144:145], off
	s_waitcnt vmcnt(6)
	s_barrier
	v_mfma_f32_16x16x32_bf16 v[28:31], v[198:201], v[160:163], v[28:31]
	v_mfma_f32_16x16x32_bf16 v[24:27], v[206:209], v[160:163], v[24:27]
	v_mfma_f32_16x16x32_bf16 v[20:23], v[198:201], v[168:171], v[20:23]
	v_mfma_f32_16x16x32_bf16 v[16:19], v[206:209], v[168:171], v[16:19]
	v_mfma_f32_16x16x32_bf16 v[12:15], v[198:201], v[176:179], v[12:15]
	v_mfma_f32_16x16x32_bf16 v[8:11], v[206:209], v[176:179], v[8:11]
	v_mfma_f32_16x16x32_bf16 v[4:7], v[198:201], v[186:189], v[4:7]
	v_mfma_f32_16x16x32_bf16 v[0:3], v[206:209], v[186:189], v[0:3]
	v_mfma_f32_16x16x32_bf16 v[28:31], v[202:205], v[164:167], v[28:31]
	v_mfma_f32_16x16x32_bf16 v[24:27], v[210:213], v[164:167], v[24:27]
	v_mfma_f32_16x16x32_bf16 v[20:23], v[202:205], v[172:175], v[20:23]
	v_mfma_f32_16x16x32_bf16 v[16:19], v[210:213], v[172:175], v[16:19]
	v_mfma_f32_16x16x32_bf16 v[12:15], v[202:205], v[180:183], v[12:15]
	v_mfma_f32_16x16x32_bf16 v[8:11], v[210:213], v[180:183], v[8:11]
	v_mfma_f32_16x16x32_bf16 v[4:7], v[202:205], v[194:197], v[4:7]
	v_mfma_f32_16x16x32_bf16 v[0:3], v[210:213], v[194:197], v[0:3]
	v_or_b32_e32 v144, 0x18000, v143
	v_add_u32_e32 v148, 0x18400, v143
	v_add_u32_e32 v152, 0x18800, v143
	v_add_u32_e32 v156, 0x18c00, v143
	s_barrier
	ds_read_b128 v[144:147], v144
	ds_read_b128 v[148:151], v148
	ds_read_b128 v[152:155], v152
	ds_read_b128 v[156:159], v156
	s_add_u32 s36, s36, 0x20000
	s_addc_u32 s37, s37, 0
	s_mov_b32 m0, s43
	v_lshl_add_u64 v[198:199], s[36:37], 0, v[132:133]
	ds_read_b128 v[160:163], v142 offset:32768
	ds_read_b128 v[164:167], v142 offset:33792
	ds_read_b128 v[168:171], v142 offset:34816
	ds_read_b128 v[172:175], v142 offset:35840
	ds_read_b128 v[176:179], v142 offset:36864
	ds_read_b128 v[180:183], v142 offset:37888
	ds_read_b128 v[186:189], v142 offset:38912
	ds_read_b128 v[194:197], v142 offset:39936
	global_load_lds_dwordx4 v[198:199], off
	v_lshl_add_u64 v[198:199], s[36:37], 0, v[130:131]
	s_mov_b32 m0, s44
	s_nop 0
	global_load_lds_dwordx4 v[198:199], off
	s_waitcnt lgkmcnt(8)
	s_barrier
	s_waitcnt lgkmcnt(0)
	s_waitcnt lgkmcnt(0)
	v_mfma_f32_16x16x32_bf16 v[124:127], v[144:147], v[160:163], v[124:127]
	v_mfma_f32_16x16x32_bf16 v[120:123], v[152:155], v[160:163], v[120:123]
	v_mfma_f32_16x16x32_bf16 v[116:119], v[144:147], v[168:171], v[116:119]
	v_mfma_f32_16x16x32_bf16 v[112:115], v[152:155], v[168:171], v[112:115]
	v_mfma_f32_16x16x32_bf16 v[108:111], v[144:147], v[176:179], v[108:111]
	v_mfma_f32_16x16x32_bf16 v[104:107], v[152:155], v[176:179], v[104:107]
	v_mfma_f32_16x16x32_bf16 v[100:103], v[144:147], v[186:189], v[100:103]
	v_mfma_f32_16x16x32_bf16 v[96:99], v[152:155], v[186:189], v[96:99]
	v_mfma_f32_16x16x32_bf16 v[124:127], v[148:151], v[164:167], v[124:127]
	v_mfma_f32_16x16x32_bf16 v[120:123], v[156:159], v[164:167], v[120:123]
	v_mfma_f32_16x16x32_bf16 v[116:119], v[148:151], v[172:175], v[116:119]
	v_mfma_f32_16x16x32_bf16 v[112:115], v[156:159], v[172:175], v[112:115]
	v_mfma_f32_16x16x32_bf16 v[108:111], v[148:151], v[180:183], v[108:111]
	v_mfma_f32_16x16x32_bf16 v[104:107], v[156:159], v[180:183], v[104:107]
	v_mfma_f32_16x16x32_bf16 v[100:103], v[148:151], v[194:197], v[100:103]
	v_mfma_f32_16x16x32_bf16 v[96:99], v[156:159], v[194:197], v[96:99]
	s_barrier
	v_or_b32_e32 v192, 0x1c000, v143
	v_add_u32_e32 v202, 0x1c400, v143
	s_mov_b32 m0, s45
	ds_read_b128 v[198:201], v192
	ds_read_b128 v[202:205], v202
	v_add_u32_e32 v192, 0x1c800, v143
	v_add_u32_e32 v210, 0x1cc00, v143
	v_lshl_add_u64 v[190:191], v[190:191], 0, s[24:25]
	ds_read_b128 v[206:209], v192
	ds_read_b128 v[210:213], v210
	global_load_lds_dwordx4 v[190:191], off
	v_lshl_add_u64 v[190:191], v[214:215], 0, s[24:25]
	s_mov_b32 m0, s46
	s_nop 0
	global_load_lds_dwordx4 v[190:191], off
	s_barrier
	s_waitcnt lgkmcnt(0)
	s_waitcnt lgkmcnt(0)
	v_mfma_f32_16x16x32_bf16 v[92:95], v[198:201], v[160:163], v[92:95]
	v_mfma_f32_16x16x32_bf16 v[88:91], v[206:209], v[160:163], v[88:91]
	v_mfma_f32_16x16x32_bf16 v[84:87], v[198:201], v[168:171], v[84:87]
	v_mfma_f32_16x16x32_bf16 v[80:83], v[206:209], v[168:171], v[80:83]
	v_mfma_f32_16x16x32_bf16 v[76:79], v[198:201], v[176:179], v[76:79]
	v_mfma_f32_16x16x32_bf16 v[72:75], v[206:209], v[176:179], v[72:75]
	v_mfma_f32_16x16x32_bf16 v[68:71], v[198:201], v[186:189], v[68:71]
	v_mfma_f32_16x16x32_bf16 v[64:67], v[206:209], v[186:189], v[64:67]
	v_mfma_f32_16x16x32_bf16 v[92:95], v[202:205], v[164:167], v[92:95]
	v_mfma_f32_16x16x32_bf16 v[88:91], v[210:213], v[164:167], v[88:91]
	v_mfma_f32_16x16x32_bf16 v[84:87], v[202:205], v[172:175], v[84:87]
	v_mfma_f32_16x16x32_bf16 v[80:83], v[210:213], v[172:175], v[80:83]
	v_mfma_f32_16x16x32_bf16 v[76:79], v[202:205], v[180:183], v[76:79]
	v_mfma_f32_16x16x32_bf16 v[72:75], v[210:213], v[180:183], v[72:75]
	v_mfma_f32_16x16x32_bf16 v[68:71], v[202:205], v[194:197], v[68:71]
	v_mfma_f32_16x16x32_bf16 v[64:67], v[210:213], v[194:197], v[64:67]
	s_mov_b32 m0, s47
	v_lshl_add_u64 v[190:191], v[216:217], 0, s[24:25]
	s_barrier
	ds_read_b128 v[160:163], v142 offset:49152
	ds_read_b128 v[164:167], v142 offset:50176
	ds_read_b128 v[168:171], v142 offset:51200
	ds_read_b128 v[172:175], v142 offset:52224
	ds_read_b128 v[176:179], v142 offset:53248
	ds_read_b128 v[180:183], v142 offset:54272
	ds_read_b128 v[186:189], v142 offset:55296
	ds_read_b128 v[194:197], v142 offset:56320
	global_load_lds_dwordx4 v[190:191], off
	v_lshl_add_u64 v[190:191], v[242:243], 0, s[24:25]
	s_mov_b32 m0, s48
	s_nop 0
	global_load_lds_dwordx4 v[190:191], off
	s_barrier
	s_waitcnt lgkmcnt(0)
	s_waitcnt lgkmcnt(0)
	v_mfma_f32_16x16x32_bf16 v[60:63], v[144:147], v[160:163], v[60:63]
	v_mfma_f32_16x16x32_bf16 v[56:59], v[152:155], v[160:163], v[56:59]
	v_mfma_f32_16x16x32_bf16 v[52:55], v[144:147], v[168:171], v[52:55]
	v_mfma_f32_16x16x32_bf16 v[48:51], v[152:155], v[168:171], v[48:51]
	v_mfma_f32_16x16x32_bf16 v[44:47], v[144:147], v[176:179], v[44:47]
	v_mfma_f32_16x16x32_bf16 v[40:43], v[152:155], v[176:179], v[40:43]
	v_mfma_f32_16x16x32_bf16 v[36:39], v[144:147], v[186:189], v[36:39]
	v_mfma_f32_16x16x32_bf16 v[32:35], v[152:155], v[186:189], v[32:35]
	v_mfma_f32_16x16x32_bf16 v[60:63], v[148:151], v[164:167], v[60:63]
	v_mfma_f32_16x16x32_bf16 v[56:59], v[156:159], v[164:167], v[56:59]
	v_mfma_f32_16x16x32_bf16 v[52:55], v[148:151], v[172:175], v[52:55]
	v_mfma_f32_16x16x32_bf16 v[48:51], v[156:159], v[172:175], v[48:51]
	v_mfma_f32_16x16x32_bf16 v[44:47], v[148:151], v[180:183], v[44:47]
	v_mfma_f32_16x16x32_bf16 v[40:43], v[156:159], v[180:183], v[40:43]
	v_mfma_f32_16x16x32_bf16 v[36:39], v[148:151], v[194:197], v[36:39]
	v_mfma_f32_16x16x32_bf16 v[32:35], v[156:159], v[194:197], v[32:35]
	s_barrier
	s_add_u32 s34, s34, 0x100080
	s_addc_u32 s35, s35, 0
	s_mov_b32 m0, s49
	v_lshl_add_u64 v[144:145], s[34:35], 0, v[184:185]
	global_load_lds_dwordx4 v[144:145], off
	v_lshl_add_u64 v[144:145], s[34:35], 0, v[128:129]
	s_mov_b32 m0, s50
	s_nop 0
	global_load_lds_dwordx4 v[144:145], off
	s_waitcnt vmcnt(6)
	s_barrier
	v_mfma_f32_16x16x32_bf16 v[28:31], v[198:201], v[160:163], v[28:31]
	v_mfma_f32_16x16x32_bf16 v[24:27], v[206:209], v[160:163], v[24:27]
	v_mfma_f32_16x16x32_bf16 v[20:23], v[198:201], v[168:171], v[20:23]
	v_mfma_f32_16x16x32_bf16 v[16:19], v[206:209], v[168:171], v[16:19]
	v_mfma_f32_16x16x32_bf16 v[12:15], v[198:201], v[176:179], v[12:15]
	v_mfma_f32_16x16x32_bf16 v[8:11], v[206:209], v[176:179], v[8:11]
	v_mfma_f32_16x16x32_bf16 v[4:7], v[198:201], v[186:189], v[4:7]
	v_mfma_f32_16x16x32_bf16 v[0:3], v[206:209], v[186:189], v[0:3]
	v_mfma_f32_16x16x32_bf16 v[28:31], v[202:205], v[164:167], v[28:31]
	v_mfma_f32_16x16x32_bf16 v[24:27], v[210:213], v[164:167], v[24:27]
	v_mfma_f32_16x16x32_bf16 v[20:23], v[202:205], v[172:175], v[20:23]
	v_mfma_f32_16x16x32_bf16 v[16:19], v[210:213], v[172:175], v[16:19]
	v_mfma_f32_16x16x32_bf16 v[12:15], v[202:205], v[180:183], v[12:15]
	v_mfma_f32_16x16x32_bf16 v[8:11], v[210:213], v[180:183], v[8:11]
	v_mfma_f32_16x16x32_bf16 v[4:7], v[202:205], v[194:197], v[4:7]
	v_mfma_f32_16x16x32_bf16 v[0:3], v[210:213], v[194:197], v[0:3]
	s_add_i32 s61, s61, 2
	s_add_u32 s30, s30, 0x100
	s_addc_u32 s31, s31, 0
	s_add_u32 s26, s26, 0x100
	s_addc_u32 s27, s27, 0
	s_cmp_gt_u32 s61, 5
	s_barrier
	s_cbranch_scc0 .LBB0_245
	s_lshl_b32 s20, s59, 4
	s_add_i32 s30, s20, s51
	s_add_i32 s34, s52, s20
	s_add_i32 s36, s53, s20
	s_ashr_i32 s31, s30, 31
	s_ashr_i32 s35, s34, 31
	s_ashr_i32 s37, s36, 31
	s_lshl_b64 s[26:27], s[30:31], 13
	s_lshl_b64 s[34:35], s[34:35], 13
	s_lshl_b64 s[36:37], s[36:37], 13
	v_cvt_pk_bf16_f32 v124, v124, v125
	v_cvt_pk_bf16_f32 v125, v126, v127
	v_cvt_pk_bf16_f32 v126, v120, v121
	v_lshl_add_u64 v[120:121], v[134:135], 0, s[26:27]
	v_cvt_pk_bf16_f32 v116, v116, v117
	v_cvt_pk_bf16_f32 v117, v118, v119
	v_cvt_pk_bf16_f32 v118, v112, v113
	v_lshl_add_u64 v[112:113], v[134:135], 0, s[34:35]
	v_cvt_pk_bf16_f32 v108, v108, v109
	v_cvt_pk_bf16_f32 v109, v110, v111
	v_cvt_pk_bf16_f32 v110, v104, v105
	v_lshl_add_u64 v[104:105], v[134:135], 0, s[36:37]
	s_add_i32 s60, s54, s20
	v_cvt_pk_bf16_f32 v92, v92, v93
	v_cvt_pk_bf16_f32 v93, v94, v95
	v_cvt_pk_bf16_f32 v94, v88, v89
	v_lshl_add_u64 v[88:89], v[136:137], 0, s[26:27]
	v_cvt_pk_bf16_f32 v84, v84, v85
	v_cvt_pk_bf16_f32 v85, v86, v87
	v_cvt_pk_bf16_f32 v86, v80, v81
	v_lshl_add_u64 v[80:81], v[136:137], 0, s[34:35]
	v_cvt_pk_bf16_f32 v76, v76, v77
	v_cvt_pk_bf16_f32 v77, v78, v79
	v_cvt_pk_bf16_f32 v78, v72, v73
	v_lshl_add_u64 v[72:73], v[136:137], 0, s[36:37]
	s_add_i32 s26, s30, 8
	s_add_i32 s34, s30, 9
	s_add_i32 s36, s30, 10
	s_add_i32 s30, s30, 11
	s_ashr_i32 s61, s60, 31
	s_ashr_i32 s27, s26, 31
	s_ashr_i32 s35, s34, 31
	s_ashr_i32 s37, s36, 31
	s_ashr_i32 s31, s30, 31
	s_lshl_b64 s[60:61], s[60:61], 13
	s_lshl_b64 s[26:27], s[26:27], 13
	s_lshl_b64 s[34:35], s[34:35], 13
	s_lshl_b64 s[36:37], s[36:37], 13
	s_lshl_b64 s[30:31], s[30:31], 13
	v_cvt_pk_bf16_f32 v100, v100, v101
	v_cvt_pk_bf16_f32 v101, v102, v103
	v_cvt_pk_bf16_f32 v102, v96, v97
	v_lshl_add_u64 v[96:97], v[134:135], 0, s[60:61]
	v_cvt_pk_bf16_f32 v68, v68, v69
	v_cvt_pk_bf16_f32 v69, v70, v71
	v_cvt_pk_bf16_f32 v70, v64, v65
	v_lshl_add_u64 v[64:65], v[136:137], 0, s[60:61]
	v_cvt_pk_bf16_f32 v60, v60, v61
	v_cvt_pk_bf16_f32 v61, v62, v63
	v_cvt_pk_bf16_f32 v62, v56, v57
	v_lshl_add_u64 v[56:57], v[134:135], 0, s[26:27]
	v_cvt_pk_bf16_f32 v52, v52, v53
	v_cvt_pk_bf16_f32 v53, v54, v55
	v_cvt_pk_bf16_f32 v54, v48, v49
	v_lshl_add_u64 v[48:49], v[134:135], 0, s[34:35]
	v_cvt_pk_bf16_f32 v44, v44, v45
	v_cvt_pk_bf16_f32 v45, v46, v47
	v_cvt_pk_bf16_f32 v46, v40, v41
	v_lshl_add_u64 v[40:41], v[134:135], 0, s[36:37]
	v_cvt_pk_bf16_f32 v36, v36, v37
	v_cvt_pk_bf16_f32 v37, v38, v39
	v_cvt_pk_bf16_f32 v38, v32, v33
	v_lshl_add_u64 v[32:33], v[134:135], 0, s[30:31]
	v_cvt_pk_bf16_f32 v28, v28, v29
	v_cvt_pk_bf16_f32 v29, v30, v31
	v_cvt_pk_bf16_f32 v30, v24, v25
	v_lshl_add_u64 v[24:25], v[136:137], 0, s[26:27]
	v_cvt_pk_bf16_f32 v20, v20, v21
	v_cvt_pk_bf16_f32 v21, v22, v23
	v_cvt_pk_bf16_f32 v22, v16, v17
	v_lshl_add_u64 v[16:17], v[136:137], 0, s[34:35]
	v_cvt_pk_bf16_f32 v12, v12, v13
	v_cvt_pk_bf16_f32 v13, v14, v15
	v_cvt_pk_bf16_f32 v14, v8, v9
	v_lshl_add_u64 v[8:9], v[136:137], 0, s[36:37]
	v_cvt_pk_bf16_f32 v4, v4, v5
	v_cvt_pk_bf16_f32 v5, v6, v7
	v_cvt_pk_bf16_f32 v6, v0, v1
	v_lshl_add_u64 v[0:1], v[136:137], 0, s[30:31]
	s_and_b64 vcc, exec, s[28:29]
	s_mov_b32 s59, s58
	v_cvt_pk_bf16_f32 v127, v122, v123
	global_store_dwordx4 v[120:121], v[124:127], off
	v_cvt_pk_bf16_f32 v119, v114, v115
	global_store_dwordx4 v[112:113], v[116:119], off
	v_cvt_pk_bf16_f32 v111, v106, v107
	global_store_dwordx4 v[104:105], v[108:111], off
	v_cvt_pk_bf16_f32 v103, v98, v99
	global_store_dwordx4 v[96:97], v[100:103], off
	v_cvt_pk_bf16_f32 v95, v90, v91
	global_store_dwordx4 v[88:89], v[92:95], off
	v_cvt_pk_bf16_f32 v87, v82, v83
	global_store_dwordx4 v[80:81], v[84:87], off
	v_cvt_pk_bf16_f32 v79, v74, v75
	global_store_dwordx4 v[72:73], v[76:79], off
	v_cvt_pk_bf16_f32 v71, v66, v67
	global_store_dwordx4 v[64:65], v[68:71], off
	v_cvt_pk_bf16_f32 v63, v58, v59
	global_store_dwordx4 v[56:57], v[60:63], off
	v_cvt_pk_bf16_f32 v55, v50, v51
	global_store_dwordx4 v[48:49], v[52:55], off
	v_cvt_pk_bf16_f32 v47, v42, v43
	global_store_dwordx4 v[40:41], v[44:47], off
	v_cvt_pk_bf16_f32 v39, v34, v35
	global_store_dwordx4 v[32:33], v[36:39], off
	v_cvt_pk_bf16_f32 v31, v26, v27
	global_store_dwordx4 v[24:25], v[28:31], off
	v_cvt_pk_bf16_f32 v23, v18, v19
	global_store_dwordx4 v[16:17], v[20:23], off
	v_cvt_pk_bf16_f32 v15, v10, v11
	global_store_dwordx4 v[8:9], v[12:15], off
	v_cvt_pk_bf16_f32 v7, v2, v3
	global_store_dwordx4 v[0:1], v[4:7], off
	s_cbranch_vccz .LBB0_244
	s_waitcnt vmcnt(0)
	s_cmpk_gt_u32 s33, 0xff
	s_cbranch_scc1 .LBB0_249
	s_barrier

.LBB0_299:
	v_or_b32_e32 v128, 0x10000, v143
	v_add_u32_e32 v152, 0x10400, v143
	v_add_u32_e32 v157, 0x10800, v143
	v_add_u32_e32 v162, 0x10c00, v143
	ds_read_b128 v[128:131], v128
	ds_read_b128 v[152:155], v152
	ds_read_b128 v[158:161], v157
	ds_read_b128 v[162:165], v162
	s_add_u32 s28, s0, 0xfffc0080
	s_addc_u32 s29, s1, -1
	s_cmp_eq_u32 s27, 12
	s_cselect_b32 s31, s20, s29
	s_cselect_b32 s30, s34, s28
	s_cselect_b32 s29, s35, s26
	s_cselect_b32 s28, s36, s37
	v_lshl_add_u64 v[182:183], s[0:1], 0, v[148:149]
	s_add_i32 m0, s58, 0xc000
	ds_read_b128 v[166:169], v141
	ds_read_b128 v[170:173], v141 offset:1024
	ds_read_b128 v[174:177], v141 offset:2048
	ds_read_b128 v[178:181], v141 offset:3072
	ds_read_b128 v[186:189], v141 offset:4096
	ds_read_b128 v[194:197], v141 offset:5120
	ds_read_b128 v[198:201], v141 offset:6144
	ds_read_b128 v[202:205], v141 offset:7168
	global_load_lds_dwordx4 v[182:183], off
	v_lshl_add_u64 v[182:183], s[0:1], 0, v[150:151]
	s_add_i32 m0, s58, 0xe000
	s_nop 0
	global_load_lds_dwordx4 v[182:183], off
	s_waitcnt lgkmcnt(8)
	s_barrier
	s_waitcnt lgkmcnt(0)
	s_waitcnt lgkmcnt(0)
	v_mfma_f32_16x16x32_bf16 v[124:127], v[128:131], v[166:169], v[124:127]
	v_mfma_f32_16x16x32_bf16 v[120:123], v[158:161], v[166:169], v[120:123]
	v_mfma_f32_16x16x32_bf16 v[116:119], v[128:131], v[174:177], v[116:119]
	v_mfma_f32_16x16x32_bf16 v[112:115], v[158:161], v[174:177], v[112:115]
	v_mfma_f32_16x16x32_bf16 v[108:111], v[128:131], v[186:189], v[108:111]
	v_mfma_f32_16x16x32_bf16 v[104:107], v[158:161], v[186:189], v[104:107]
	v_mfma_f32_16x16x32_bf16 v[100:103], v[128:131], v[198:201], v[100:103]
	v_mfma_f32_16x16x32_bf16 v[96:99], v[158:161], v[198:201], v[96:99]
	v_mfma_f32_16x16x32_bf16 v[124:127], v[152:155], v[170:173], v[124:127]
	v_mfma_f32_16x16x32_bf16 v[120:123], v[162:165], v[170:173], v[120:123]
	v_mfma_f32_16x16x32_bf16 v[116:119], v[152:155], v[178:181], v[116:119]
	v_mfma_f32_16x16x32_bf16 v[112:115], v[162:165], v[178:181], v[112:115]
	v_mfma_f32_16x16x32_bf16 v[108:111], v[152:155], v[194:197], v[108:111]
	v_mfma_f32_16x16x32_bf16 v[104:107], v[162:165], v[194:197], v[104:107]
	v_mfma_f32_16x16x32_bf16 v[100:103], v[152:155], v[202:205], v[100:103]
	v_mfma_f32_16x16x32_bf16 v[96:99], v[162:165], v[202:205], v[96:99]
	s_barrier
	v_or_b32_e32 v157, 0x14000, v143
	v_add_u32_e32 v182, 0x14400, v143
	ds_read_b128 v[206:209], v157
	ds_read_b128 v[210:213], v182
	v_add_u32_e32 v157, 0x14800, v143
	v_add_u32_e32 v182, 0x14c00, v143
	s_mov_b32 m0, s39
	ds_read_b128 v[214:217], v157
	ds_read_b128 v[242:245], v182
	v_lshl_add_u64 v[182:183], s[28:29], 0, v[134:135]
	global_load_lds_dwordx4 v[182:183], off
	v_lshl_add_u64 v[190:191], s[28:29], 0, v[138:139]
	s_mov_b32 m0, s59
	s_nop 0
	global_load_lds_dwordx4 v[190:191], off
	s_barrier
	s_waitcnt lgkmcnt(0)
	s_waitcnt lgkmcnt(0)
	v_mfma_f32_16x16x32_bf16 v[92:95], v[206:209], v[166:169], v[92:95]
	v_mfma_f32_16x16x32_bf16 v[88:91], v[214:217], v[166:169], v[88:91]
	v_mfma_f32_16x16x32_bf16 v[84:87], v[206:209], v[174:177], v[84:87]
	v_mfma_f32_16x16x32_bf16 v[80:83], v[214:217], v[174:177], v[80:83]
	v_mfma_f32_16x16x32_bf16 v[76:79], v[206:209], v[186:189], v[76:79]
	v_mfma_f32_16x16x32_bf16 v[72:75], v[214:217], v[186:189], v[72:75]
	v_mfma_f32_16x16x32_bf16 v[68:71], v[206:209], v[198:201], v[68:71]
	v_mfma_f32_16x16x32_bf16 v[64:67], v[214:217], v[198:201], v[64:67]
	v_mfma_f32_16x16x32_bf16 v[92:95], v[210:213], v[170:173], v[92:95]
	v_mfma_f32_16x16x32_bf16 v[88:91], v[242:245], v[170:173], v[88:91]
	v_mfma_f32_16x16x32_bf16 v[84:87], v[210:213], v[178:181], v[84:87]
	v_mfma_f32_16x16x32_bf16 v[80:83], v[242:245], v[178:181], v[80:83]
	v_mfma_f32_16x16x32_bf16 v[76:79], v[210:213], v[194:197], v[76:79]
	v_mfma_f32_16x16x32_bf16 v[72:75], v[242:245], v[194:197], v[72:75]
	v_mfma_f32_16x16x32_bf16 v[68:71], v[210:213], v[202:205], v[68:71]
	v_mfma_f32_16x16x32_bf16 v[64:67], v[242:245], v[202:205], v[64:67]
	s_mov_b32 m0, s58
	v_lshl_add_u64 v[246:247], s[30:31], 0, v[132:133]
	s_barrier
	ds_read_b128 v[166:169], v141 offset:16384
	ds_read_b128 v[170:173], v141 offset:17408
	ds_read_b128 v[174:177], v141 offset:18432
	ds_read_b128 v[178:181], v141 offset:19456
	ds_read_b128 v[186:189], v141 offset:20480
	ds_read_b128 v[194:197], v141 offset:21504
	ds_read_b128 v[198:201], v141 offset:22528
	ds_read_b128 v[202:205], v141 offset:23552
	global_load_lds_dwordx4 v[246:247], off
	v_lshl_add_u64 v[248:249], s[30:31], 0, v[136:137]
	s_mov_b32 m0, s60
	s_nop 0
	global_load_lds_dwordx4 v[248:249], off
	s_barrier
	s_waitcnt lgkmcnt(0)
	s_waitcnt lgkmcnt(0)
	v_mfma_f32_16x16x32_bf16 v[60:63], v[128:131], v[166:169], v[60:63]
	v_mfma_f32_16x16x32_bf16 v[56:59], v[158:161], v[166:169], v[56:59]
	v_mfma_f32_16x16x32_bf16 v[52:55], v[128:131], v[174:177], v[52:55]
	v_mfma_f32_16x16x32_bf16 v[48:51], v[158:161], v[174:177], v[48:51]
	v_mfma_f32_16x16x32_bf16 v[44:47], v[128:131], v[186:189], v[44:47]
	v_mfma_f32_16x16x32_bf16 v[40:43], v[158:161], v[186:189], v[40:43]
	v_mfma_f32_16x16x32_bf16 v[36:39], v[128:131], v[198:201], v[36:39]
	v_mfma_f32_16x16x32_bf16 v[32:35], v[158:161], v[198:201], v[32:35]
	v_mfma_f32_16x16x32_bf16 v[60:63], v[152:155], v[170:173], v[60:63]
	v_mfma_f32_16x16x32_bf16 v[56:59], v[162:165], v[170:173], v[56:59]
	v_mfma_f32_16x16x32_bf16 v[52:55], v[152:155], v[178:181], v[52:55]
	v_mfma_f32_16x16x32_bf16 v[48:51], v[162:165], v[178:181], v[48:51]
	v_mfma_f32_16x16x32_bf16 v[44:47], v[152:155], v[194:197], v[44:47]
	v_mfma_f32_16x16x32_bf16 v[40:43], v[162:165], v[194:197], v[40:43]
	v_mfma_f32_16x16x32_bf16 v[36:39], v[152:155], v[202:205], v[36:39]
	v_mfma_f32_16x16x32_bf16 v[32:35], v[162:165], v[202:205], v[32:35]
	s_barrier
	s_add_u32 s46, s28, 0x40000
	s_addc_u32 s47, s29, 0
	s_mov_b32 m0, s61
	v_lshl_add_u64 v[128:129], s[46:47], 0, v[134:135]
	global_load_lds_dwordx4 v[128:129], off
	v_lshl_add_u64 v[128:129], s[46:47], 0, v[138:139]
	s_mov_b32 m0, s62
	s_nop 0
	global_load_lds_dwordx4 v[128:129], off
	s_waitcnt vmcnt(6)
	s_barrier
	v_mfma_f32_16x16x32_bf16 v[28:31], v[206:209], v[166:169], v[28:31]
	v_mfma_f32_16x16x32_bf16 v[24:27], v[214:217], v[166:169], v[24:27]
	v_mfma_f32_16x16x32_bf16 v[20:23], v[206:209], v[174:177], v[20:23]
	v_mfma_f32_16x16x32_bf16 v[16:19], v[214:217], v[174:177], v[16:19]
	v_mfma_f32_16x16x32_bf16 v[12:15], v[206:209], v[186:189], v[12:15]
	v_mfma_f32_16x16x32_bf16 v[8:11], v[214:217], v[186:189], v[8:11]
	v_mfma_f32_16x16x32_bf16 v[4:7], v[206:209], v[198:201], v[4:7]
	v_mfma_f32_16x16x32_bf16 v[0:3], v[214:217], v[198:201], v[0:3]
	v_mfma_f32_16x16x32_bf16 v[28:31], v[210:213], v[170:173], v[28:31]
	v_mfma_f32_16x16x32_bf16 v[24:27], v[242:245], v[170:173], v[24:27]
	v_mfma_f32_16x16x32_bf16 v[20:23], v[210:213], v[178:181], v[20:23]
	v_mfma_f32_16x16x32_bf16 v[16:19], v[242:245], v[178:181], v[16:19]
	v_mfma_f32_16x16x32_bf16 v[12:15], v[210:213], v[194:197], v[12:15]
	v_mfma_f32_16x16x32_bf16 v[8:11], v[242:245], v[194:197], v[8:11]
	v_mfma_f32_16x16x32_bf16 v[4:7], v[210:213], v[202:205], v[4:7]
	v_mfma_f32_16x16x32_bf16 v[0:3], v[242:245], v[202:205], v[0:3]
	v_or_b32_e32 v128, 0x18000, v143
	v_add_u32_e32 v152, 0x18400, v143
	v_add_u32_e32 v157, 0x18800, v143
	v_add_u32_e32 v162, 0x18c00, v143
	s_barrier
	ds_read_b128 v[128:131], v128
	ds_read_b128 v[152:155], v152
	ds_read_b128 v[158:161], v157
	ds_read_b128 v[162:165], v162
	s_add_u32 s30, s30, 0x40000
	s_addc_u32 s31, s31, 0
	s_mov_b32 m0, s63
	v_lshl_add_u64 v[206:207], s[30:31], 0, v[132:133]
	ds_read_b128 v[166:169], v141 offset:32768
	ds_read_b128 v[170:173], v141 offset:33792
	ds_read_b128 v[174:177], v141 offset:34816
	ds_read_b128 v[178:181], v141 offset:35840
	ds_read_b128 v[186:189], v141 offset:36864
	ds_read_b128 v[194:197], v141 offset:37888
	ds_read_b128 v[198:201], v141 offset:38912
	ds_read_b128 v[202:205], v141 offset:39936
	global_load_lds_dwordx4 v[206:207], off
	v_lshl_add_u64 v[206:207], s[30:31], 0, v[136:137]
	s_mov_b32 m0, s64
	s_nop 0
	global_load_lds_dwordx4 v[206:207], off
	s_waitcnt lgkmcnt(8)
	s_barrier
	s_waitcnt lgkmcnt(0)
	s_waitcnt lgkmcnt(0)
	v_mfma_f32_16x16x32_bf16 v[124:127], v[128:131], v[166:169], v[124:127]
	v_mfma_f32_16x16x32_bf16 v[120:123], v[158:161], v[166:169], v[120:123]
	v_mfma_f32_16x16x32_bf16 v[116:119], v[128:131], v[174:177], v[116:119]
	v_mfma_f32_16x16x32_bf16 v[112:115], v[158:161], v[174:177], v[112:115]
	v_mfma_f32_16x16x32_bf16 v[108:111], v[128:131], v[186:189], v[108:111]
	v_mfma_f32_16x16x32_bf16 v[104:107], v[158:161], v[186:189], v[104:107]
	v_mfma_f32_16x16x32_bf16 v[100:103], v[128:131], v[198:201], v[100:103]
	v_mfma_f32_16x16x32_bf16 v[96:99], v[158:161], v[198:201], v[96:99]
	v_mfma_f32_16x16x32_bf16 v[124:127], v[152:155], v[170:173], v[124:127]
	v_mfma_f32_16x16x32_bf16 v[120:123], v[162:165], v[170:173], v[120:123]
	v_mfma_f32_16x16x32_bf16 v[116:119], v[152:155], v[178:181], v[116:119]
	v_mfma_f32_16x16x32_bf16 v[112:115], v[162:165], v[178:181], v[112:115]
	v_mfma_f32_16x16x32_bf16 v[108:111], v[152:155], v[194:197], v[108:111]
	v_mfma_f32_16x16x32_bf16 v[104:107], v[162:165], v[194:197], v[104:107]
	v_mfma_f32_16x16x32_bf16 v[100:103], v[152:155], v[202:205], v[100:103]
	v_mfma_f32_16x16x32_bf16 v[96:99], v[162:165], v[202:205], v[96:99]
	s_barrier
	v_or_b32_e32 v157, 0x1c000, v143
	s_mov_b32 m0, s68
	v_add_u32_e32 v184, 0x1c400, v143
	ds_read_b128 v[206:209], v157
	ds_read_b128 v[210:213], v184
	v_add_u32_e32 v157, 0x1c800, v143
	v_lshl_add_u64 v[182:183], v[182:183], 0, s[24:25]
	v_add_u32_e32 v184, 0x1cc00, v143
	ds_read_b128 v[214:217], v157
	ds_read_b128 v[242:245], v184
	global_load_lds_dwordx4 v[182:183], off
	v_lshl_add_u64 v[182:183], v[190:191], 0, s[24:25]
	s_mov_b32 m0, s69
	s_nop 0
	global_load_lds_dwordx4 v[182:183], off
	s_barrier
	s_waitcnt lgkmcnt(0)
	s_waitcnt lgkmcnt(0)
	v_mfma_f32_16x16x32_bf16 v[92:95], v[206:209], v[166:169], v[92:95]
	v_mfma_f32_16x16x32_bf16 v[88:91], v[214:217], v[166:169], v[88:91]
	v_mfma_f32_16x16x32_bf16 v[84:87], v[206:209], v[174:177], v[84:87]
	v_mfma_f32_16x16x32_bf16 v[80:83], v[214:217], v[174:177], v[80:83]
	v_mfma_f32_16x16x32_bf16 v[76:79], v[206:209], v[186:189], v[76:79]
	v_mfma_f32_16x16x32_bf16 v[72:75], v[214:217], v[186:189], v[72:75]
	v_mfma_f32_16x16x32_bf16 v[68:71], v[206:209], v[198:201], v[68:71]
	v_mfma_f32_16x16x32_bf16 v[64:67], v[214:217], v[198:201], v[64:67]
	v_mfma_f32_16x16x32_bf16 v[92:95], v[210:213], v[170:173], v[92:95]
	v_mfma_f32_16x16x32_bf16 v[88:91], v[242:245], v[170:173], v[88:91]
	v_mfma_f32_16x16x32_bf16 v[84:87], v[210:213], v[178:181], v[84:87]
	v_mfma_f32_16x16x32_bf16 v[80:83], v[242:245], v[178:181], v[80:83]
	v_mfma_f32_16x16x32_bf16 v[76:79], v[210:213], v[194:197], v[76:79]
	v_mfma_f32_16x16x32_bf16 v[72:75], v[242:245], v[194:197], v[72:75]
	v_mfma_f32_16x16x32_bf16 v[68:71], v[210:213], v[202:205], v[68:71]
	v_mfma_f32_16x16x32_bf16 v[64:67], v[242:245], v[202:205], v[64:67]
	s_mov_b32 m0, s70
	v_lshl_add_u64 v[182:183], v[246:247], 0, s[24:25]
	s_barrier
	ds_read_b128 v[166:169], v141 offset:49152
	ds_read_b128 v[170:173], v141 offset:50176
	ds_read_b128 v[174:177], v141 offset:51200
	ds_read_b128 v[178:181], v141 offset:52224
	ds_read_b128 v[186:189], v141 offset:53248
	ds_read_b128 v[194:197], v141 offset:54272
	ds_read_b128 v[198:201], v141 offset:55296
	ds_read_b128 v[202:205], v141 offset:56320
	global_load_lds_dwordx4 v[182:183], off
	v_lshl_add_u64 v[182:183], v[248:249], 0, s[24:25]
	s_mov_b32 m0, s71
	s_nop 0
	global_load_lds_dwordx4 v[182:183], off
	s_barrier
	s_waitcnt lgkmcnt(0)
	s_waitcnt lgkmcnt(0)
	v_mfma_f32_16x16x32_bf16 v[60:63], v[128:131], v[166:169], v[60:63]
	v_mfma_f32_16x16x32_bf16 v[56:59], v[158:161], v[166:169], v[56:59]
	v_mfma_f32_16x16x32_bf16 v[52:55], v[128:131], v[174:177], v[52:55]
	v_mfma_f32_16x16x32_bf16 v[48:51], v[158:161], v[174:177], v[48:51]
	v_mfma_f32_16x16x32_bf16 v[44:47], v[128:131], v[186:189], v[44:47]
	v_mfma_f32_16x16x32_bf16 v[40:43], v[158:161], v[186:189], v[40:43]
	v_mfma_f32_16x16x32_bf16 v[36:39], v[128:131], v[198:201], v[36:39]
	v_mfma_f32_16x16x32_bf16 v[32:35], v[158:161], v[198:201], v[32:35]
	v_mfma_f32_16x16x32_bf16 v[60:63], v[152:155], v[170:173], v[60:63]
	v_mfma_f32_16x16x32_bf16 v[56:59], v[162:165], v[170:173], v[56:59]
	v_mfma_f32_16x16x32_bf16 v[52:55], v[152:155], v[178:181], v[52:55]
	v_mfma_f32_16x16x32_bf16 v[48:51], v[162:165], v[178:181], v[48:51]
	v_mfma_f32_16x16x32_bf16 v[44:47], v[152:155], v[194:197], v[44:47]
	v_mfma_f32_16x16x32_bf16 v[40:43], v[162:165], v[194:197], v[40:43]
	v_mfma_f32_16x16x32_bf16 v[36:39], v[152:155], v[202:205], v[36:39]
	v_mfma_f32_16x16x32_bf16 v[32:35], v[162:165], v[202:205], v[32:35]
	s_barrier
	s_add_u32 s28, s28, 0x40080
	s_addc_u32 s29, s29, 0
	s_mov_b32 m0, s52
	v_lshl_add_u64 v[128:129], s[28:29], 0, v[134:135]
	global_load_lds_dwordx4 v[128:129], off
	v_lshl_add_u64 v[128:129], s[28:29], 0, v[138:139]
	s_mov_b32 m0, s50
	s_nop 0
	global_load_lds_dwordx4 v[128:129], off
	s_waitcnt vmcnt(6)
	s_barrier
	v_mfma_f32_16x16x32_bf16 v[28:31], v[206:209], v[166:169], v[28:31]
	v_mfma_f32_16x16x32_bf16 v[24:27], v[214:217], v[166:169], v[24:27]
	v_mfma_f32_16x16x32_bf16 v[20:23], v[206:209], v[174:177], v[20:23]
	v_mfma_f32_16x16x32_bf16 v[16:19], v[214:217], v[174:177], v[16:19]
	v_mfma_f32_16x16x32_bf16 v[12:15], v[206:209], v[186:189], v[12:15]
	v_mfma_f32_16x16x32_bf16 v[8:11], v[214:217], v[186:189], v[8:11]
	v_mfma_f32_16x16x32_bf16 v[4:7], v[206:209], v[198:201], v[4:7]
	v_mfma_f32_16x16x32_bf16 v[0:3], v[214:217], v[198:201], v[0:3]
	v_mfma_f32_16x16x32_bf16 v[28:31], v[210:213], v[170:173], v[28:31]
	v_mfma_f32_16x16x32_bf16 v[24:27], v[242:245], v[170:173], v[24:27]
	v_mfma_f32_16x16x32_bf16 v[20:23], v[210:213], v[178:181], v[20:23]
	v_mfma_f32_16x16x32_bf16 v[16:19], v[242:245], v[178:181], v[16:19]
	v_mfma_f32_16x16x32_bf16 v[12:15], v[210:213], v[194:197], v[12:15]
	v_mfma_f32_16x16x32_bf16 v[8:11], v[242:245], v[194:197], v[8:11]
	v_mfma_f32_16x16x32_bf16 v[4:7], v[210:213], v[202:205], v[4:7]
	v_mfma_f32_16x16x32_bf16 v[0:3], v[242:245], v[202:205], v[0:3]
	s_add_i32 s27, s27, 2
	s_add_u32 s0, s0, 0x100
	s_addc_u32 s1, s1, 0
	s_add_u32 s37, s37, 0x100
	s_addc_u32 s26, s26, 0
	s_cmp_gt_u32 s27, 13
	s_barrier
	s_cbranch_scc0 .LBB0_299
	s_lshl_b32 s20, s53, 8
	s_add_i32 s20, s20, s66
	s_lshl_b32 s46, s38, 8
	s_cmp_lg_u32 s33, 0
	v_or_b32_e32 v154, s20, v140
	v_or_b32_e32 v152, s46, v144
	s_cselect_b64 s[28:29], -1, 0
	s_movk_i32 s33, 0x3fff
	s_and_b64 vcc, exec, s[28:29]
	v_and_b32_e32 v157, 0xcf, v154
	v_cmp_lt_i32_e64 s[0:1], s33, v152
	s_cbranch_vccz .LBB0_306
	s_ashr_i32 s30, s20, 8
	v_cvt_pk_bf16_f32 v128, v124, v125
	v_cvt_pk_bf16_f32 v129, v126, v127
	v_cvt_pk_bf16_f32 v130, v120, v121
	v_cvt_pk_bf16_f32 v131, v122, v123
	s_and_saveexec_b64 s[26:27], s[0:1]
	s_xor_b64 s[0:1], exec, s[26:27]
	s_cbranch_execz .LBB0_303
	s_add_i32 s26, s46, 0xffffc000
	s_lshr_b32 s26, s26, 7
	v_lshl_add_u32 v184, v157, 4, s26
	s_ashr_i32 s31, s30, 31
	v_lshl_add_u64 v[158:159], v[184:185], 0, s[30:31]
	v_lshlrev_b64 v[158:159], 9, v[158:159]
	v_lshl_add_u64 v[158:159], v[146:147], 0, v[158:159]
	global_store_dwordx4 v[158:159], v[128:131], off
